# K loops: loop-control and next-iteration head SALU moved in front of the loop-back barrier (back-edge rotation, up/gelu/QKV full, resid control only)
# baseline (speedup 1.0000x reference)
.Lwpf_skip:
	s_ashr_i32 s21, s20, 31
	s_lshl_b64 s[22:23], s[20:21], 19
	s_add_u32 s22, s80, s22
	s_addc_u32 s23, s81, s23
	s_and_b64 s[24:25], s[2:3], exec
	s_cselect_b32 s5, s23, s29
	s_cselect_b32 s21, s22, s28
	s_ashr_i32 s19, s18, 31
	s_lshl_b64 s[24:25], s[18:19], 18
	s_add_u32 s24, s33, s24
	s_addc_u32 s25, s36, s25
	s_and_b64 s[34:35], s[2:3], exec
	s_cselect_b32 s19, s25, s31
	s_cselect_b32 s27, s24, s30
	s_add_u32 s28, s28, 0x40080
	s_addc_u32 s29, s29, 0
	s_add_u32 s60, s30, 0x100
	v_mov_b32_e32 v6, 0
	s_addc_u32 s61, s31, 0
	s_mov_b32 s62, -2
	v_mov_b32_e32 v7, v6
	v_mov_b64_e32 v[8:9], 0
	v_mov_b64_e32 v[10:11], 0
	v_mov_b64_e32 v[12:13], 0
	v_mov_b64_e32 v[22:23], 0
	v_mov_b64_e32 v[24:25], 0
	v_mov_b64_e32 v[26:27], 0
	v_mov_b64_e32 v[28:29], 0
	v_mov_b64_e32 v[38:39], 0
	v_mov_b64_e32 v[40:41], 0
	v_mov_b64_e32 v[42:43], 0
	v_mov_b64_e32 v[44:45], 0
	v_mov_b64_e32 v[54:55], 0
	v_mov_b64_e32 v[56:57], 0
	v_mov_b64_e32 v[58:59], 0
	v_mov_b64_e32 v[60:61], 0
	v_mov_b64_e32 v[14:15], 0
	v_mov_b64_e32 v[16:17], 0
	v_mov_b64_e32 v[18:19], 0
	v_mov_b64_e32 v[20:21], 0
	v_mov_b64_e32 v[30:31], 0
	v_mov_b64_e32 v[32:33], 0
	v_mov_b64_e32 v[34:35], 0
	v_mov_b64_e32 v[36:37], 0
	v_mov_b64_e32 v[46:47], 0
	v_mov_b64_e32 v[48:49], 0
	v_mov_b64_e32 v[50:51], 0
	v_mov_b64_e32 v[52:53], 0
	v_mov_b64_e32 v[62:63], 0
	v_mov_b64_e32 v[64:65], 0
	v_mov_b64_e32 v[66:67], 0
	v_mov_b64_e32 v[68:69], 0
	v_mov_b64_e32 v[70:71], 0
	v_mov_b64_e32 v[72:73], 0
	v_mov_b64_e32 v[74:75], 0
	v_mov_b64_e32 v[76:77], 0
	v_mov_b64_e32 v[86:87], 0
	v_mov_b64_e32 v[88:89], 0
	v_mov_b64_e32 v[90:91], 0
	v_mov_b64_e32 v[92:93], 0
	v_mov_b64_e32 v[102:103], 0
	v_mov_b64_e32 v[104:105], 0
	v_mov_b64_e32 v[106:107], 0
	v_mov_b64_e32 v[108:109], 0
	v_mov_b64_e32 v[118:119], 0
	v_mov_b64_e32 v[120:121], 0
	v_mov_b64_e32 v[122:123], 0
	v_mov_b64_e32 v[124:125], 0
	v_mov_b64_e32 v[78:79], 0
	v_mov_b64_e32 v[80:81], 0
	v_mov_b64_e32 v[82:83], 0
	v_mov_b64_e32 v[84:85], 0
	v_mov_b64_e32 v[94:95], 0
	v_mov_b64_e32 v[96:97], 0
	v_mov_b64_e32 v[98:99], 0
	v_mov_b64_e32 v[100:101], 0
	v_mov_b64_e32 v[110:111], 0
	v_mov_b64_e32 v[112:113], 0
	v_mov_b64_e32 v[114:115], 0
	v_mov_b64_e32 v[116:117], 0
	v_mov_b64_e32 v[126:127], 0
	v_mov_b64_e32 v[128:129], 0
	v_mov_b64_e32 v[130:131], 0
	v_mov_b64_e32 v[132:133], 0
	s_add_u32 s30, s28, 0xfffc0080
	s_addc_u32 s31, s29, -1
	s_add_i32 s63, 0, 0x10000
	s_cmp_eq_u32 s62, 12
	s_cselect_b32 s35, s5, s31
	s_cselect_b32 s34, s21, s30
	s_cselect_b32 s31, s19, s61
	s_cselect_b32 s30, s27, s60
	s_add_i32 s66, 0, 0x14000
.LBB0_79:
	v_add_u32_e32 v146, s63, v148
	ds_read_b128 v[142:145], v146
	ds_read_b128 v[152:155], v146 offset:1024
	ds_read_b128 v[156:159], v146 offset:2048
	ds_read_b128 v[160:163], v146 offset:3072
	v_add_u32_e32 v146, s66, v148
	ds_read_b128 v[164:167], v146
	ds_read_b128 v[168:171], v146 offset:1024
	ds_read_b128 v[172:175], v146 offset:2048
	ds_read_b128 v[176:179], v146 offset:3072
	v_lshl_add_u64 v[146:147], s[28:29], 0, v[138:139]
	s_add_i32 m0, s38, 0xc000
	ds_read_b128 v[180:183], v150
	ds_read_b128 v[184:187], v150 offset:1024
	ds_read_b128 v[188:191], v150 offset:2048
	ds_read_b128 v[192:195], v150 offset:3072
	ds_read_b128 v[196:199], v150 offset:4096
	ds_read_b128 v[200:203], v150 offset:5120
	ds_read_b128 v[204:207], v150 offset:6144
	ds_read_b128 v[208:211], v150 offset:7168
	global_load_lds_dwordx4 v[146:147], off
	v_lshl_add_u64 v[146:147], s[28:29], 0, v[140:141]
	s_add_i32 m0, s38, 0xe000
	s_nop 0
	global_load_lds_dwordx4 v[146:147], off
	s_waitcnt vmcnt(8)
	s_waitcnt lgkmcnt(0)
	s_barrier
	s_setprio 1
	s_waitcnt lgkmcnt(0)
	v_mfma_f32_16x16x32_bf16 v[130:133], v[142:145], v[180:183], v[130:133]
	v_mfma_f32_16x16x32_bf16 v[126:129], v[156:159], v[180:183], v[126:129]
	v_mfma_f32_16x16x32_bf16 v[114:117], v[142:145], v[188:191], v[114:117]
	v_mfma_f32_16x16x32_bf16 v[110:113], v[156:159], v[188:191], v[110:113]
	v_mfma_f32_16x16x32_bf16 v[98:101], v[142:145], v[196:199], v[98:101]
	v_mfma_f32_16x16x32_bf16 v[94:97], v[156:159], v[196:199], v[94:97]
	v_mfma_f32_16x16x32_bf16 v[82:85], v[142:145], v[204:207], v[82:85]
	v_mfma_f32_16x16x32_bf16 v[78:81], v[156:159], v[204:207], v[78:81]
	v_mfma_f32_16x16x32_bf16 v[130:133], v[152:155], v[184:187], v[130:133]
	v_mfma_f32_16x16x32_bf16 v[126:129], v[160:163], v[184:187], v[126:129]
	v_mfma_f32_16x16x32_bf16 v[114:117], v[152:155], v[192:195], v[114:117]
	v_mfma_f32_16x16x32_bf16 v[110:113], v[160:163], v[192:195], v[110:113]
	v_mfma_f32_16x16x32_bf16 v[98:101], v[152:155], v[200:203], v[98:101]
	v_mfma_f32_16x16x32_bf16 v[94:97], v[160:163], v[200:203], v[94:97]
	v_mfma_f32_16x16x32_bf16 v[82:85], v[152:155], v[208:211], v[82:85]
	v_mfma_f32_16x16x32_bf16 v[78:81], v[160:163], v[208:211], v[78:81]
	s_setprio 0
	s_setprio 1
	v_mfma_f32_16x16x32_bf16 v[122:125], v[164:167], v[180:183], v[122:125]
	v_mfma_f32_16x16x32_bf16 v[118:121], v[172:175], v[180:183], v[118:121]
	v_mfma_f32_16x16x32_bf16 v[106:109], v[164:167], v[188:191], v[106:109]
	v_mfma_f32_16x16x32_bf16 v[102:105], v[172:175], v[188:191], v[102:105]
	v_mfma_f32_16x16x32_bf16 v[90:93], v[164:167], v[196:199], v[90:93]
	v_mfma_f32_16x16x32_bf16 v[86:89], v[172:175], v[196:199], v[86:89]
	v_mfma_f32_16x16x32_bf16 v[74:77], v[164:167], v[204:207], v[74:77]
	v_mfma_f32_16x16x32_bf16 v[70:73], v[172:175], v[204:207], v[70:73]
	v_mfma_f32_16x16x32_bf16 v[122:125], v[168:171], v[184:187], v[122:125]
	v_mfma_f32_16x16x32_bf16 v[118:121], v[176:179], v[184:187], v[118:121]
	v_mfma_f32_16x16x32_bf16 v[106:109], v[168:171], v[192:195], v[106:109]
	v_mfma_f32_16x16x32_bf16 v[102:105], v[176:179], v[192:195], v[102:105]
	v_mfma_f32_16x16x32_bf16 v[90:93], v[168:171], v[200:203], v[90:93]
	v_mfma_f32_16x16x32_bf16 v[86:89], v[176:179], v[200:203], v[86:89]
	v_mfma_f32_16x16x32_bf16 v[74:77], v[168:171], v[208:211], v[74:77]
	v_mfma_f32_16x16x32_bf16 v[70:73], v[176:179], v[208:211], v[70:73]
	s_setprio 0
	s_barrier
	s_add_i32 s63, s63, s37
	v_lshl_add_u64 v[146:147], s[30:31], 0, v[0:1]
	s_mov_b32 m0, s63
	ds_read_b128 v[180:183], v150 offset:16384
	ds_read_b128 v[184:187], v150 offset:17408
	ds_read_b128 v[188:191], v150 offset:18432
	ds_read_b128 v[192:195], v150 offset:19456
	ds_read_b128 v[196:199], v150 offset:20480
	ds_read_b128 v[200:203], v150 offset:21504
	ds_read_b128 v[204:207], v150 offset:22528
	ds_read_b128 v[208:211], v150 offset:23552
	global_load_lds_dwordx4 v[146:147], off
	s_add_i32 m0, s63, 0x2000
	s_add_u32 s64, s30, 0x580000
	v_lshl_add_u64 v[212:213], s[30:31], 0, v[136:137]
	s_addc_u32 s65, s31, 0
	s_add_i32 s63, s66, s37
	global_load_lds_dwordx4 v[212:213], off
	v_lshl_add_u64 v[214:215], s[64:65], 0, v[0:1]
	s_mov_b32 m0, s63
	v_lshl_add_u64 v[216:217], s[34:35], 0, v[134:135]
	global_load_lds_dwordx4 v[214:215], off
	v_lshl_add_u64 v[214:215], s[64:65], 0, v[136:137]
	s_add_i32 m0, s63, 0x2000
	s_nop 0
	global_load_lds_dwordx4 v[214:215], off
	v_lshl_add_u64 v[214:215], s[34:35], 0, v[2:3]
	s_mov_b32 m0, s38
	s_nop 0
	global_load_lds_dwordx4 v[214:215], off
	s_mov_b32 m0, s39
	s_nop 0
	global_load_lds_dwordx4 v[216:217], off
	s_waitcnt vmcnt(8)
	s_waitcnt lgkmcnt(0)
	s_barrier
	s_setprio 1
	s_waitcnt lgkmcnt(0)
	v_mfma_f32_16x16x32_bf16 v[66:69], v[142:145], v[180:183], v[66:69]
	v_mfma_f32_16x16x32_bf16 v[62:65], v[156:159], v[180:183], v[62:65]
	v_mfma_f32_16x16x32_bf16 v[50:53], v[142:145], v[188:191], v[50:53]
	v_mfma_f32_16x16x32_bf16 v[46:49], v[156:159], v[188:191], v[46:49]
	v_mfma_f32_16x16x32_bf16 v[34:37], v[142:145], v[196:199], v[34:37]
	v_mfma_f32_16x16x32_bf16 v[30:33], v[156:159], v[196:199], v[30:33]
	v_mfma_f32_16x16x32_bf16 v[18:21], v[142:145], v[204:207], v[18:21]
	v_mfma_f32_16x16x32_bf16 v[14:17], v[156:159], v[204:207], v[14:17]
	v_mfma_f32_16x16x32_bf16 v[66:69], v[152:155], v[184:187], v[66:69]
	v_mfma_f32_16x16x32_bf16 v[62:65], v[160:163], v[184:187], v[62:65]
	v_mfma_f32_16x16x32_bf16 v[50:53], v[152:155], v[192:195], v[50:53]
	v_mfma_f32_16x16x32_bf16 v[46:49], v[160:163], v[192:195], v[46:49]
	v_mfma_f32_16x16x32_bf16 v[34:37], v[152:155], v[200:203], v[34:37]
	v_mfma_f32_16x16x32_bf16 v[30:33], v[160:163], v[200:203], v[30:33]
	v_mfma_f32_16x16x32_bf16 v[18:21], v[152:155], v[208:211], v[18:21]
	v_mfma_f32_16x16x32_bf16 v[14:17], v[160:163], v[208:211], v[14:17]
	s_setprio 0
	s_setprio 1
	v_mfma_f32_16x16x32_bf16 v[58:61], v[164:167], v[180:183], v[58:61]
	v_mfma_f32_16x16x32_bf16 v[54:57], v[172:175], v[180:183], v[54:57]
	v_mfma_f32_16x16x32_bf16 v[42:45], v[164:167], v[188:191], v[42:45]
	v_mfma_f32_16x16x32_bf16 v[38:41], v[172:175], v[188:191], v[38:41]
	v_mfma_f32_16x16x32_bf16 v[26:29], v[164:167], v[196:199], v[26:29]
	v_mfma_f32_16x16x32_bf16 v[22:25], v[172:175], v[196:199], v[22:25]
	v_mfma_f32_16x16x32_bf16 v[10:13], v[164:167], v[204:207], v[10:13]
	v_mfma_f32_16x16x32_bf16 v[6:9], v[172:175], v[204:207], v[6:9]
	v_mfma_f32_16x16x32_bf16 v[58:61], v[168:171], v[184:187], v[58:61]
	v_mfma_f32_16x16x32_bf16 v[54:57], v[176:179], v[184:187], v[54:57]
	v_mfma_f32_16x16x32_bf16 v[42:45], v[168:171], v[192:195], v[42:45]
	v_mfma_f32_16x16x32_bf16 v[38:41], v[176:179], v[192:195], v[38:41]
	v_mfma_f32_16x16x32_bf16 v[26:29], v[168:171], v[200:203], v[26:29]
	v_mfma_f32_16x16x32_bf16 v[22:25], v[176:179], v[200:203], v[22:25]
	v_mfma_f32_16x16x32_bf16 v[10:13], v[168:171], v[208:211], v[10:13]
	v_mfma_f32_16x16x32_bf16 v[6:9], v[176:179], v[208:211], v[6:9]
	s_setprio 0
	s_barrier
	s_add_i32 s63, 0, 0x18000
	v_add_u32_e32 v151, s63, v148
	s_add_i32 s64, 0, 0x1c000
	ds_read_b128 v[142:145], v151
	ds_read_b128 v[152:155], v151 offset:1024
	ds_read_b128 v[156:159], v151 offset:2048
	ds_read_b128 v[160:163], v151 offset:3072
	v_add_u32_e32 v151, s64, v148
	ds_read_b128 v[164:167], v151
	ds_read_b128 v[168:171], v151 offset:1024
	ds_read_b128 v[172:175], v151 offset:2048
	ds_read_b128 v[176:179], v151 offset:3072
	s_add_u32 s34, s34, 0x40000
	s_addc_u32 s35, s35, 0
	s_mov_b32 m0, s41
	v_lshl_add_u64 v[220:221], s[34:35], 0, v[2:3]
	ds_read_b128 v[180:183], v150 offset:32768
	ds_read_b128 v[184:187], v150 offset:33792
	ds_read_b128 v[188:191], v150 offset:34816
	ds_read_b128 v[192:195], v150 offset:35840
	ds_read_b128 v[196:199], v150 offset:36864
	ds_read_b128 v[200:203], v150 offset:37888
	ds_read_b128 v[204:207], v150 offset:38912
	ds_read_b128 v[208:211], v150 offset:39936
	global_load_lds_dwordx4 v[220:221], off
	v_lshl_add_u64 v[220:221], s[34:35], 0, v[134:135]
	s_mov_b32 m0, s42
	s_nop 0
	global_load_lds_dwordx4 v[220:221], off
	s_waitcnt vmcnt(8)
	s_waitcnt lgkmcnt(0)
	s_barrier
	s_setprio 1
	s_waitcnt lgkmcnt(0)
	v_mfma_f32_16x16x32_bf16 v[130:133], v[142:145], v[180:183], v[130:133]
	v_mfma_f32_16x16x32_bf16 v[126:129], v[156:159], v[180:183], v[126:129]
	v_mfma_f32_16x16x32_bf16 v[114:117], v[142:145], v[188:191], v[114:117]
	v_mfma_f32_16x16x32_bf16 v[110:113], v[156:159], v[188:191], v[110:113]
	v_mfma_f32_16x16x32_bf16 v[98:101], v[142:145], v[196:199], v[98:101]
	v_mfma_f32_16x16x32_bf16 v[94:97], v[156:159], v[196:199], v[94:97]
	v_mfma_f32_16x16x32_bf16 v[82:85], v[142:145], v[204:207], v[82:85]
	v_mfma_f32_16x16x32_bf16 v[78:81], v[156:159], v[204:207], v[78:81]
	v_mfma_f32_16x16x32_bf16 v[130:133], v[152:155], v[184:187], v[130:133]
	v_mfma_f32_16x16x32_bf16 v[126:129], v[160:163], v[184:187], v[126:129]
	v_mfma_f32_16x16x32_bf16 v[114:117], v[152:155], v[192:195], v[114:117]
	v_mfma_f32_16x16x32_bf16 v[110:113], v[160:163], v[192:195], v[110:113]
	v_mfma_f32_16x16x32_bf16 v[98:101], v[152:155], v[200:203], v[98:101]
	v_mfma_f32_16x16x32_bf16 v[94:97], v[160:163], v[200:203], v[94:97]
	v_mfma_f32_16x16x32_bf16 v[82:85], v[152:155], v[208:211], v[82:85]
	v_mfma_f32_16x16x32_bf16 v[78:81], v[160:163], v[208:211], v[78:81]
	s_setprio 0
	s_setprio 1
	v_mfma_f32_16x16x32_bf16 v[122:125], v[164:167], v[180:183], v[122:125]
	v_mfma_f32_16x16x32_bf16 v[118:121], v[172:175], v[180:183], v[118:121]
	v_mfma_f32_16x16x32_bf16 v[106:109], v[164:167], v[188:191], v[106:109]
	v_mfma_f32_16x16x32_bf16 v[102:105], v[172:175], v[188:191], v[102:105]
	v_mfma_f32_16x16x32_bf16 v[90:93], v[164:167], v[196:199], v[90:93]
	v_mfma_f32_16x16x32_bf16 v[86:89], v[172:175], v[196:199], v[86:89]
	v_mfma_f32_16x16x32_bf16 v[74:77], v[164:167], v[204:207], v[74:77]
	v_mfma_f32_16x16x32_bf16 v[70:73], v[172:175], v[204:207], v[70:73]
	v_mfma_f32_16x16x32_bf16 v[122:125], v[168:171], v[184:187], v[122:125]
	v_mfma_f32_16x16x32_bf16 v[118:121], v[176:179], v[184:187], v[118:121]
	v_mfma_f32_16x16x32_bf16 v[106:109], v[168:171], v[192:195], v[106:109]
	v_mfma_f32_16x16x32_bf16 v[102:105], v[176:179], v[192:195], v[102:105]
	v_mfma_f32_16x16x32_bf16 v[90:93], v[168:171], v[200:203], v[90:93]
	v_mfma_f32_16x16x32_bf16 v[86:89], v[176:179], v[200:203], v[86:89]
	v_mfma_f32_16x16x32_bf16 v[74:77], v[168:171], v[208:211], v[74:77]
	v_mfma_f32_16x16x32_bf16 v[70:73], v[176:179], v[208:211], v[70:73]
	s_setprio 0
	s_barrier
	s_add_i32 s34, s63, s37
	v_lshl_add_u64 v[146:147], v[146:147], 0, s[50:51]
	s_mov_b32 m0, s34
	ds_read_b128 v[180:183], v150 offset:49152
	ds_read_b128 v[184:187], v150 offset:50176
	ds_read_b128 v[188:191], v150 offset:51200
	ds_read_b128 v[192:195], v150 offset:52224
	ds_read_b128 v[196:199], v150 offset:53248
	ds_read_b128 v[200:203], v150 offset:54272
	ds_read_b128 v[204:207], v150 offset:55296
	ds_read_b128 v[208:211], v150 offset:56320
	global_load_lds_dwordx4 v[146:147], off
	s_add_i32 m0, s34, 0x2000
	s_add_u32 s30, s30, 0x580080
	v_lshl_add_u64 v[146:147], v[212:213], 0, s[50:51]
	s_addc_u32 s31, s31, 0
	s_add_i32 s34, s64, s37
	global_load_lds_dwordx4 v[146:147], off
	v_lshl_add_u64 v[146:147], s[30:31], 0, v[0:1]
	s_mov_b32 m0, s34
	s_nop 0
	global_load_lds_dwordx4 v[146:147], off
	v_lshl_add_u64 v[146:147], s[30:31], 0, v[136:137]
	s_add_i32 m0, s34, 0x2000
	s_nop 0
	global_load_lds_dwordx4 v[146:147], off
	v_lshl_add_u64 v[146:147], v[214:215], 0, s[50:51]
	s_mov_b32 m0, s44
	s_nop 0
	global_load_lds_dwordx4 v[146:147], off
	v_lshl_add_u64 v[146:147], v[216:217], 0, s[50:51]
	s_mov_b32 m0, s45
	s_nop 0
	global_load_lds_dwordx4 v[146:147], off
	s_waitcnt vmcnt(8)
	s_waitcnt lgkmcnt(0)
	s_barrier
	s_setprio 1
	s_waitcnt lgkmcnt(0)
	v_mfma_f32_16x16x32_bf16 v[66:69], v[142:145], v[180:183], v[66:69]
	v_mfma_f32_16x16x32_bf16 v[62:65], v[156:159], v[180:183], v[62:65]
	v_mfma_f32_16x16x32_bf16 v[50:53], v[142:145], v[188:191], v[50:53]
	v_mfma_f32_16x16x32_bf16 v[46:49], v[156:159], v[188:191], v[46:49]
	v_mfma_f32_16x16x32_bf16 v[34:37], v[142:145], v[196:199], v[34:37]
	v_mfma_f32_16x16x32_bf16 v[30:33], v[156:159], v[196:199], v[30:33]
	v_mfma_f32_16x16x32_bf16 v[18:21], v[142:145], v[204:207], v[18:21]
	v_mfma_f32_16x16x32_bf16 v[14:17], v[156:159], v[204:207], v[14:17]
	v_mfma_f32_16x16x32_bf16 v[66:69], v[152:155], v[184:187], v[66:69]
	v_mfma_f32_16x16x32_bf16 v[62:65], v[160:163], v[184:187], v[62:65]
	v_mfma_f32_16x16x32_bf16 v[50:53], v[152:155], v[192:195], v[50:53]
	v_mfma_f32_16x16x32_bf16 v[46:49], v[160:163], v[192:195], v[46:49]
	v_mfma_f32_16x16x32_bf16 v[34:37], v[152:155], v[200:203], v[34:37]
	v_mfma_f32_16x16x32_bf16 v[30:33], v[160:163], v[200:203], v[30:33]
	v_mfma_f32_16x16x32_bf16 v[18:21], v[152:155], v[208:211], v[18:21]
	v_mfma_f32_16x16x32_bf16 v[14:17], v[160:163], v[208:211], v[14:17]
	s_setprio 0
	s_setprio 1
	v_mfma_f32_16x16x32_bf16 v[58:61], v[164:167], v[180:183], v[58:61]
	v_mfma_f32_16x16x32_bf16 v[54:57], v[172:175], v[180:183], v[54:57]
	v_mfma_f32_16x16x32_bf16 v[42:45], v[164:167], v[188:191], v[42:45]
	v_mfma_f32_16x16x32_bf16 v[38:41], v[172:175], v[188:191], v[38:41]
	v_mfma_f32_16x16x32_bf16 v[26:29], v[164:167], v[196:199], v[26:29]
	v_mfma_f32_16x16x32_bf16 v[22:25], v[172:175], v[196:199], v[22:25]
	v_mfma_f32_16x16x32_bf16 v[10:13], v[164:167], v[204:207], v[10:13]
	v_mfma_f32_16x16x32_bf16 v[6:9], v[172:175], v[204:207], v[6:9]
	v_mfma_f32_16x16x32_bf16 v[58:61], v[168:171], v[184:187], v[58:61]
	v_mfma_f32_16x16x32_bf16 v[54:57], v[176:179], v[184:187], v[54:57]
	v_mfma_f32_16x16x32_bf16 v[42:45], v[168:171], v[192:195], v[42:45]
	v_mfma_f32_16x16x32_bf16 v[38:41], v[176:179], v[192:195], v[38:41]
	v_mfma_f32_16x16x32_bf16 v[26:29], v[168:171], v[200:203], v[26:29]
	v_mfma_f32_16x16x32_bf16 v[22:25], v[176:179], v[200:203], v[22:25]
	v_mfma_f32_16x16x32_bf16 v[10:13], v[168:171], v[208:211], v[10:13]
	v_mfma_f32_16x16x32_bf16 v[6:9], v[176:179], v[208:211], v[6:9]
	s_setprio 0
	s_add_i32 s62, s62, 2
	s_add_u32 s28, s28, 0x100
	s_addc_u32 s29, s29, 0
	s_add_u32 s60, s60, 0x100
	s_addc_u32 s61, s61, 0
	s_add_u32 s30, s28, 0xfffc0080
	s_addc_u32 s31, s29, -1
	s_add_i32 s63, 0, 0x10000
	s_cmp_eq_u32 s62, 12
	s_cselect_b32 s35, s5, s31
	s_cselect_b32 s34, s21, s30
	s_cselect_b32 s31, s19, s61
	s_cselect_b32 s30, s27, s60
	s_add_i32 s66, 0, 0x14000
	s_cmp_gt_u32 s62, 13
	s_barrier
	s_cbranch_scc0 .LBB0_79
	s_and_b64 vcc, exec, s[16:17]
	s_cbranch_vccz .LBB0_82
	s_barrier

.LBB0_204:
	s_ashr_i32 s19, s18, 31
	s_lshl_b64 s[20:21], s[18:19], 19
	s_add_u32 s20, s80, s20
	s_addc_u32 s21, s81, s21
	s_and_b64 s[22:23], s[4:5], exec
	s_cselect_b32 s7, s21, s27
	s_cselect_b32 s19, s20, s26
	s_ashr_i32 s17, s16, 31
	s_lshl_b64 s[22:23], s[16:17], 19
	s_add_u32 s22, s33, s22
	s_addc_u32 s23, s34, s23
	s_and_b64 s[30:31], s[4:5], exec
	s_cselect_b32 s17, s23, s29
	s_cselect_b32 s25, s22, s28
	s_add_u32 s26, s26, 0x40080
	s_addc_u32 s27, s27, 0
	s_add_u32 s48, s28, 0x100
	v_mov_b32_e32 v6, 0
	s_addc_u32 s58, s29, 0
	s_mov_b32 s59, -2
	v_mov_b32_e32 v7, v6
	v_mov_b64_e32 v[8:9], 0
	v_mov_b64_e32 v[10:11], 0
	v_mov_b64_e32 v[12:13], 0
	v_mov_b64_e32 v[22:23], 0
	v_mov_b64_e32 v[24:25], 0
	v_mov_b64_e32 v[26:27], 0
	v_mov_b64_e32 v[28:29], 0
	v_mov_b64_e32 v[38:39], 0
	v_mov_b64_e32 v[40:41], 0
	v_mov_b64_e32 v[42:43], 0
	v_mov_b64_e32 v[44:45], 0
	v_mov_b64_e32 v[70:71], 0
	v_mov_b64_e32 v[72:73], 0
	v_mov_b64_e32 v[74:75], 0
	v_mov_b64_e32 v[76:77], 0
	v_mov_b64_e32 v[14:15], 0
	v_mov_b64_e32 v[16:17], 0
	v_mov_b64_e32 v[18:19], 0
	v_mov_b64_e32 v[20:21], 0
	v_mov_b64_e32 v[30:31], 0
	v_mov_b64_e32 v[32:33], 0
	v_mov_b64_e32 v[34:35], 0
	v_mov_b64_e32 v[36:37], 0
	v_mov_b64_e32 v[62:63], 0
	v_mov_b64_e32 v[64:65], 0
	v_mov_b64_e32 v[66:67], 0
	v_mov_b64_e32 v[68:69], 0
	v_mov_b64_e32 v[78:79], 0
	v_mov_b64_e32 v[80:81], 0
	v_mov_b64_e32 v[82:83], 0
	v_mov_b64_e32 v[84:85], 0
	v_mov_b64_e32 v[86:87], 0
	v_mov_b64_e32 v[88:89], 0
	v_mov_b64_e32 v[90:91], 0
	v_mov_b64_e32 v[92:93], 0
	v_mov_b64_e32 v[102:103], 0
	v_mov_b64_e32 v[104:105], 0
	v_mov_b64_e32 v[106:107], 0
	v_mov_b64_e32 v[108:109], 0
	v_mov_b64_e32 v[118:119], 0
	v_mov_b64_e32 v[120:121], 0
	v_mov_b64_e32 v[122:123], 0
	v_mov_b64_e32 v[124:125], 0
	v_mov_b64_e32 v[134:135], 0
	v_mov_b64_e32 v[136:137], 0
	v_mov_b64_e32 v[138:139], 0
	v_mov_b64_e32 v[140:141], 0
	v_mov_b64_e32 v[94:95], 0
	v_mov_b64_e32 v[96:97], 0
	v_mov_b64_e32 v[98:99], 0
	v_mov_b64_e32 v[100:101], 0
	v_mov_b64_e32 v[110:111], 0
	v_mov_b64_e32 v[112:113], 0
	v_mov_b64_e32 v[114:115], 0
	v_mov_b64_e32 v[116:117], 0
	v_mov_b64_e32 v[126:127], 0
	v_mov_b64_e32 v[128:129], 0
	v_mov_b64_e32 v[130:131], 0
	v_mov_b64_e32 v[132:133], 0
	v_mov_b64_e32 v[142:143], 0
	v_mov_b64_e32 v[144:145], 0
	v_mov_b64_e32 v[146:147], 0
	v_mov_b64_e32 v[148:149], 0
	s_add_u32 s28, s26, 0xfffc0080
	s_addc_u32 s29, s27, -1
	s_add_i32 s60, 0, 0x10000
	s_cmp_eq_u32 s59, 12
	s_cselect_b32 s31, s7, s29
	s_cselect_b32 s30, s19, s28
	s_cselect_b32 s29, s17, s58
	s_cselect_b32 s28, s25, s48
	s_add_i32 s62, 0, 0x14000
.LBB0_205:
	v_add_u32_e32 v0, s60, v164
	ds_read_b128 v[46:49], v0
	ds_read_b128 v[50:53], v0 offset:1024
	ds_read_b128 v[54:57], v0 offset:2048
	ds_read_b128 v[58:61], v0 offset:3072
	v_add_u32_e32 v0, s62, v164
	ds_read_b128 v[160:163], v0
	ds_read_b128 v[168:171], v0 offset:1024
	ds_read_b128 v[172:175], v0 offset:2048
	ds_read_b128 v[176:179], v0 offset:3072
	v_lshl_add_u64 v[212:213], s[26:27], 0, v[156:157]
	s_add_i32 m0, s36, 0xc000
	ds_read_b128 v[180:183], v166
	ds_read_b128 v[184:187], v166 offset:1024
	ds_read_b128 v[188:191], v166 offset:2048
	ds_read_b128 v[192:195], v166 offset:3072
	ds_read_b128 v[196:199], v166 offset:4096
	ds_read_b128 v[200:203], v166 offset:5120
	ds_read_b128 v[204:207], v166 offset:6144
	ds_read_b128 v[208:211], v166 offset:7168
	global_load_lds_dwordx4 v[212:213], off
	v_lshl_add_u64 v[212:213], s[26:27], 0, v[158:159]
	s_add_i32 m0, s36, 0xe000
	s_nop 0
	global_load_lds_dwordx4 v[212:213], off
	s_waitcnt vmcnt(8)
	s_waitcnt lgkmcnt(0)
	s_barrier
	s_setprio 1
	s_waitcnt lgkmcnt(0)
	v_mfma_f32_16x16x32_bf16 v[146:149], v[46:49], v[180:183], v[146:149]
	v_mfma_f32_16x16x32_bf16 v[142:145], v[54:57], v[180:183], v[142:145]
	v_mfma_f32_16x16x32_bf16 v[130:133], v[46:49], v[188:191], v[130:133]
	v_mfma_f32_16x16x32_bf16 v[126:129], v[54:57], v[188:191], v[126:129]
	v_mfma_f32_16x16x32_bf16 v[114:117], v[46:49], v[196:199], v[114:117]
	v_mfma_f32_16x16x32_bf16 v[110:113], v[54:57], v[196:199], v[110:113]
	v_mfma_f32_16x16x32_bf16 v[98:101], v[46:49], v[204:207], v[98:101]
	v_mfma_f32_16x16x32_bf16 v[94:97], v[54:57], v[204:207], v[94:97]
	v_mfma_f32_16x16x32_bf16 v[146:149], v[50:53], v[184:187], v[146:149]
	v_mfma_f32_16x16x32_bf16 v[142:145], v[58:61], v[184:187], v[142:145]
	v_mfma_f32_16x16x32_bf16 v[130:133], v[50:53], v[192:195], v[130:133]
	v_mfma_f32_16x16x32_bf16 v[126:129], v[58:61], v[192:195], v[126:129]
	v_mfma_f32_16x16x32_bf16 v[114:117], v[50:53], v[200:203], v[114:117]
	v_mfma_f32_16x16x32_bf16 v[110:113], v[58:61], v[200:203], v[110:113]
	v_mfma_f32_16x16x32_bf16 v[98:101], v[50:53], v[208:211], v[98:101]
	v_mfma_f32_16x16x32_bf16 v[94:97], v[58:61], v[208:211], v[94:97]
	s_setprio 0
	s_setprio 1
	v_mfma_f32_16x16x32_bf16 v[138:141], v[160:163], v[180:183], v[138:141]
	v_mfma_f32_16x16x32_bf16 v[134:137], v[172:175], v[180:183], v[134:137]
	v_mfma_f32_16x16x32_bf16 v[122:125], v[160:163], v[188:191], v[122:125]
	v_mfma_f32_16x16x32_bf16 v[118:121], v[172:175], v[188:191], v[118:121]
	v_mfma_f32_16x16x32_bf16 v[106:109], v[160:163], v[196:199], v[106:109]
	v_mfma_f32_16x16x32_bf16 v[102:105], v[172:175], v[196:199], v[102:105]
	v_mfma_f32_16x16x32_bf16 v[90:93], v[160:163], v[204:207], v[90:93]
	v_mfma_f32_16x16x32_bf16 v[86:89], v[172:175], v[204:207], v[86:89]
	v_mfma_f32_16x16x32_bf16 v[138:141], v[168:171], v[184:187], v[138:141]
	v_mfma_f32_16x16x32_bf16 v[134:137], v[176:179], v[184:187], v[134:137]
	v_mfma_f32_16x16x32_bf16 v[122:125], v[168:171], v[192:195], v[122:125]
	v_mfma_f32_16x16x32_bf16 v[118:121], v[176:179], v[192:195], v[118:121]
	v_mfma_f32_16x16x32_bf16 v[106:109], v[168:171], v[200:203], v[106:109]
	v_mfma_f32_16x16x32_bf16 v[102:105], v[176:179], v[200:203], v[102:105]
	v_mfma_f32_16x16x32_bf16 v[90:93], v[168:171], v[208:211], v[90:93]
	v_mfma_f32_16x16x32_bf16 v[86:89], v[176:179], v[208:211], v[86:89]
	s_setprio 0
	s_barrier
	s_add_i32 s60, s60, s35
	v_lshl_add_u64 v[212:213], s[28:29], 0, v[150:151]
	s_mov_b32 m0, s60
	ds_read_b128 v[180:183], v166 offset:16384
	ds_read_b128 v[184:187], v166 offset:17408
	ds_read_b128 v[188:191], v166 offset:18432
	ds_read_b128 v[192:195], v166 offset:19456
	ds_read_b128 v[196:199], v166 offset:20480
	ds_read_b128 v[200:203], v166 offset:21504
	ds_read_b128 v[204:207], v166 offset:22528
	ds_read_b128 v[208:211], v166 offset:23552
	global_load_lds_dwordx4 v[212:213], off
	s_add_i32 m0, s60, 0x2000
	s_add_u32 s60, s28, 0x40000
	v_lshl_add_u64 v[214:215], s[28:29], 0, v[154:155]
	s_addc_u32 s61, s29, 0
	s_add_i32 s62, s62, s35
	global_load_lds_dwordx4 v[214:215], off
	v_lshl_add_u64 v[216:217], s[60:61], 0, v[150:151]
	s_mov_b32 m0, s62
	v_lshl_add_u64 v[220:221], s[30:31], 0, v[152:153]
	global_load_lds_dwordx4 v[216:217], off
	v_lshl_add_u64 v[216:217], s[60:61], 0, v[154:155]
	s_add_i32 m0, s62, 0x2000
	s_nop 0
	global_load_lds_dwordx4 v[216:217], off
	v_lshl_add_u64 v[216:217], s[30:31], 0, v[2:3]
	s_mov_b32 m0, s36
	s_nop 0
	global_load_lds_dwordx4 v[216:217], off
	s_mov_b32 m0, s37
	s_nop 0
	global_load_lds_dwordx4 v[220:221], off
	s_waitcnt vmcnt(8)
	s_waitcnt lgkmcnt(0)
	s_barrier
	s_setprio 1
	s_waitcnt lgkmcnt(0)
	v_mfma_f32_16x16x32_bf16 v[82:85], v[46:49], v[180:183], v[82:85]
	v_mfma_f32_16x16x32_bf16 v[78:81], v[54:57], v[180:183], v[78:81]
	v_mfma_f32_16x16x32_bf16 v[66:69], v[46:49], v[188:191], v[66:69]
	v_mfma_f32_16x16x32_bf16 v[62:65], v[54:57], v[188:191], v[62:65]
	v_mfma_f32_16x16x32_bf16 v[34:37], v[46:49], v[196:199], v[34:37]
	v_mfma_f32_16x16x32_bf16 v[30:33], v[54:57], v[196:199], v[30:33]
	v_mfma_f32_16x16x32_bf16 v[18:21], v[46:49], v[204:207], v[18:21]
	v_mfma_f32_16x16x32_bf16 v[14:17], v[54:57], v[204:207], v[14:17]
	v_mfma_f32_16x16x32_bf16 v[82:85], v[50:53], v[184:187], v[82:85]
	v_mfma_f32_16x16x32_bf16 v[78:81], v[58:61], v[184:187], v[78:81]
	v_mfma_f32_16x16x32_bf16 v[66:69], v[50:53], v[192:195], v[66:69]
	v_mfma_f32_16x16x32_bf16 v[62:65], v[58:61], v[192:195], v[62:65]
	v_mfma_f32_16x16x32_bf16 v[34:37], v[50:53], v[200:203], v[34:37]
	v_mfma_f32_16x16x32_bf16 v[30:33], v[58:61], v[200:203], v[30:33]
	v_mfma_f32_16x16x32_bf16 v[18:21], v[50:53], v[208:211], v[18:21]
	v_mfma_f32_16x16x32_bf16 v[14:17], v[58:61], v[208:211], v[14:17]
	s_setprio 0
	s_setprio 1
	v_mfma_f32_16x16x32_bf16 v[42:45], v[160:163], v[188:191], v[42:45]
	v_mfma_f32_16x16x32_bf16 v[38:41], v[172:175], v[188:191], v[38:41]
	v_mfma_f32_16x16x32_bf16 v[26:29], v[160:163], v[196:199], v[26:29]
	v_mfma_f32_16x16x32_bf16 v[22:25], v[172:175], v[196:199], v[22:25]
	v_mfma_f32_16x16x32_bf16 v[10:13], v[160:163], v[204:207], v[10:13]
	v_mfma_f32_16x16x32_bf16 v[6:9], v[172:175], v[204:207], v[6:9]
	v_mfma_f32_16x16x32_bf16 v[46:49], v[160:163], v[180:183], v[74:77]
	v_mfma_f32_16x16x32_bf16 v[50:53], v[172:175], v[180:183], v[70:73]
	v_mfma_f32_16x16x32_bf16 v[42:45], v[168:171], v[192:195], v[42:45]
	v_mfma_f32_16x16x32_bf16 v[38:41], v[176:179], v[192:195], v[38:41]
	v_mfma_f32_16x16x32_bf16 v[26:29], v[168:171], v[200:203], v[26:29]
	v_mfma_f32_16x16x32_bf16 v[22:25], v[176:179], v[200:203], v[22:25]
	v_mfma_f32_16x16x32_bf16 v[10:13], v[168:171], v[208:211], v[10:13]
	v_mfma_f32_16x16x32_bf16 v[6:9], v[176:179], v[208:211], v[6:9]
	v_mfma_f32_16x16x32_bf16 v[46:49], v[168:171], v[184:187], v[46:49]
	v_mfma_f32_16x16x32_bf16 v[50:53], v[176:179], v[184:187], v[50:53]
	s_setprio 0
	s_barrier
	s_add_i32 s60, 0, 0x18000
	v_add_u32_e32 v0, s60, v164
	s_add_i32 s61, 0, 0x1c000
	ds_read_b128 v[54:57], v0
	ds_read_b128 v[58:61], v0 offset:1024
	ds_read_b128 v[70:73], v0 offset:2048
	ds_read_b128 v[74:77], v0 offset:3072
	v_add_u32_e32 v0, s61, v164
	ds_read_b128 v[160:163], v0
	ds_read_b128 v[168:171], v0 offset:1024
	ds_read_b128 v[172:175], v0 offset:2048
	ds_read_b128 v[176:179], v0 offset:3072
	s_add_u32 s30, s30, 0x40000
	s_addc_u32 s31, s31, 0
	s_mov_b32 m0, s38
	v_lshl_add_u64 v[222:223], s[30:31], 0, v[2:3]
	ds_read_b128 v[180:183], v166 offset:32768
	ds_read_b128 v[184:187], v166 offset:33792
	ds_read_b128 v[188:191], v166 offset:34816
	ds_read_b128 v[192:195], v166 offset:35840
	ds_read_b128 v[196:199], v166 offset:36864
	ds_read_b128 v[200:203], v166 offset:37888
	ds_read_b128 v[204:207], v166 offset:38912
	ds_read_b128 v[208:211], v166 offset:39936
	global_load_lds_dwordx4 v[222:223], off
	v_lshl_add_u64 v[222:223], s[30:31], 0, v[152:153]
	s_mov_b32 m0, s39
	s_nop 0
	global_load_lds_dwordx4 v[222:223], off
	s_waitcnt vmcnt(8)
	s_waitcnt lgkmcnt(0)
	s_barrier
	s_setprio 1
	s_waitcnt lgkmcnt(0)
	v_mfma_f32_16x16x32_bf16 v[146:149], v[54:57], v[180:183], v[146:149]
	v_mfma_f32_16x16x32_bf16 v[142:145], v[70:73], v[180:183], v[142:145]
	v_mfma_f32_16x16x32_bf16 v[130:133], v[54:57], v[188:191], v[130:133]
	v_mfma_f32_16x16x32_bf16 v[126:129], v[70:73], v[188:191], v[126:129]
	v_mfma_f32_16x16x32_bf16 v[114:117], v[54:57], v[196:199], v[114:117]
	v_mfma_f32_16x16x32_bf16 v[110:113], v[70:73], v[196:199], v[110:113]
	v_mfma_f32_16x16x32_bf16 v[98:101], v[54:57], v[204:207], v[98:101]
	v_mfma_f32_16x16x32_bf16 v[94:97], v[70:73], v[204:207], v[94:97]
	v_mfma_f32_16x16x32_bf16 v[146:149], v[58:61], v[184:187], v[146:149]
	v_mfma_f32_16x16x32_bf16 v[142:145], v[74:77], v[184:187], v[142:145]
	v_mfma_f32_16x16x32_bf16 v[130:133], v[58:61], v[192:195], v[130:133]
	v_mfma_f32_16x16x32_bf16 v[126:129], v[74:77], v[192:195], v[126:129]
	v_mfma_f32_16x16x32_bf16 v[114:117], v[58:61], v[200:203], v[114:117]
	v_mfma_f32_16x16x32_bf16 v[110:113], v[74:77], v[200:203], v[110:113]
	v_mfma_f32_16x16x32_bf16 v[98:101], v[58:61], v[208:211], v[98:101]
	v_mfma_f32_16x16x32_bf16 v[94:97], v[74:77], v[208:211], v[94:97]
	s_setprio 0
	s_setprio 1
	v_mfma_f32_16x16x32_bf16 v[138:141], v[160:163], v[180:183], v[138:141]
	v_mfma_f32_16x16x32_bf16 v[134:137], v[172:175], v[180:183], v[134:137]
	v_mfma_f32_16x16x32_bf16 v[122:125], v[160:163], v[188:191], v[122:125]
	v_mfma_f32_16x16x32_bf16 v[118:121], v[172:175], v[188:191], v[118:121]
	v_mfma_f32_16x16x32_bf16 v[106:109], v[160:163], v[196:199], v[106:109]
	v_mfma_f32_16x16x32_bf16 v[102:105], v[172:175], v[196:199], v[102:105]
	v_mfma_f32_16x16x32_bf16 v[90:93], v[160:163], v[204:207], v[90:93]
	v_mfma_f32_16x16x32_bf16 v[86:89], v[172:175], v[204:207], v[86:89]
	v_mfma_f32_16x16x32_bf16 v[138:141], v[168:171], v[184:187], v[138:141]
	v_mfma_f32_16x16x32_bf16 v[134:137], v[176:179], v[184:187], v[134:137]
	v_mfma_f32_16x16x32_bf16 v[122:125], v[168:171], v[192:195], v[122:125]
	v_mfma_f32_16x16x32_bf16 v[118:121], v[176:179], v[192:195], v[118:121]
	v_mfma_f32_16x16x32_bf16 v[106:109], v[168:171], v[200:203], v[106:109]
	v_mfma_f32_16x16x32_bf16 v[102:105], v[176:179], v[200:203], v[102:105]
	v_mfma_f32_16x16x32_bf16 v[90:93], v[168:171], v[208:211], v[90:93]
	v_mfma_f32_16x16x32_bf16 v[86:89], v[176:179], v[208:211], v[86:89]
	s_setprio 0
	s_barrier
	s_add_i32 s30, s60, s35
	v_lshl_add_u64 v[212:213], v[212:213], 0, s[50:51]
	s_mov_b32 m0, s30
	ds_read_b128 v[180:183], v166 offset:49152
	ds_read_b128 v[184:187], v166 offset:50176
	ds_read_b128 v[188:191], v166 offset:51200
	ds_read_b128 v[192:195], v166 offset:52224
	ds_read_b128 v[196:199], v166 offset:53248
	ds_read_b128 v[200:203], v166 offset:54272
	ds_read_b128 v[204:207], v166 offset:55296
	ds_read_b128 v[208:211], v166 offset:56320
	global_load_lds_dwordx4 v[212:213], off
	s_add_i32 m0, s30, 0x2000
	s_add_u32 s28, s28, 0x40080
	v_lshl_add_u64 v[212:213], v[214:215], 0, s[50:51]
	s_addc_u32 s29, s29, 0
	s_add_i32 s30, s61, s35
	global_load_lds_dwordx4 v[212:213], off
	v_lshl_add_u64 v[212:213], s[28:29], 0, v[150:151]
	s_mov_b32 m0, s30
	s_nop 0
	global_load_lds_dwordx4 v[212:213], off
	v_lshl_add_u64 v[212:213], s[28:29], 0, v[154:155]
	s_add_i32 m0, s30, 0x2000
	s_nop 0
	global_load_lds_dwordx4 v[212:213], off
	v_lshl_add_u64 v[212:213], v[216:217], 0, s[50:51]
	s_mov_b32 m0, s41
	s_nop 0
	global_load_lds_dwordx4 v[212:213], off
	v_lshl_add_u64 v[212:213], v[220:221], 0, s[50:51]
	s_mov_b32 m0, s42
	s_nop 0
	global_load_lds_dwordx4 v[212:213], off
	s_waitcnt vmcnt(8)
	s_waitcnt lgkmcnt(0)
	s_barrier
	s_setprio 1
	s_waitcnt lgkmcnt(0)
	v_mfma_f32_16x16x32_bf16 v[82:85], v[54:57], v[180:183], v[82:85]
	v_mfma_f32_16x16x32_bf16 v[78:81], v[70:73], v[180:183], v[78:81]
	v_mfma_f32_16x16x32_bf16 v[66:69], v[54:57], v[188:191], v[66:69]
	v_mfma_f32_16x16x32_bf16 v[62:65], v[70:73], v[188:191], v[62:65]
	v_mfma_f32_16x16x32_bf16 v[34:37], v[54:57], v[196:199], v[34:37]
	v_mfma_f32_16x16x32_bf16 v[30:33], v[70:73], v[196:199], v[30:33]
	v_mfma_f32_16x16x32_bf16 v[18:21], v[54:57], v[204:207], v[18:21]
	v_mfma_f32_16x16x32_bf16 v[14:17], v[70:73], v[204:207], v[14:17]
	v_mfma_f32_16x16x32_bf16 v[82:85], v[58:61], v[184:187], v[82:85]
	v_mfma_f32_16x16x32_bf16 v[78:81], v[74:77], v[184:187], v[78:81]
	v_mfma_f32_16x16x32_bf16 v[66:69], v[58:61], v[192:195], v[66:69]
	v_mfma_f32_16x16x32_bf16 v[62:65], v[74:77], v[192:195], v[62:65]
	v_mfma_f32_16x16x32_bf16 v[34:37], v[58:61], v[200:203], v[34:37]
	v_mfma_f32_16x16x32_bf16 v[30:33], v[74:77], v[200:203], v[30:33]
	v_mfma_f32_16x16x32_bf16 v[18:21], v[58:61], v[208:211], v[18:21]
	v_mfma_f32_16x16x32_bf16 v[14:17], v[74:77], v[208:211], v[14:17]
	s_setprio 0
	s_setprio 1
	v_mfma_f32_16x16x32_bf16 v[46:49], v[160:163], v[180:183], v[46:49]
	v_mfma_f32_16x16x32_bf16 v[74:77], v[168:171], v[184:187], v[46:49]
	v_mfma_f32_16x16x32_bf16 v[46:49], v[172:175], v[180:183], v[50:53]
	v_mfma_f32_16x16x32_bf16 v[42:45], v[160:163], v[188:191], v[42:45]
	v_mfma_f32_16x16x32_bf16 v[38:41], v[172:175], v[188:191], v[38:41]
	v_mfma_f32_16x16x32_bf16 v[26:29], v[160:163], v[196:199], v[26:29]
	v_mfma_f32_16x16x32_bf16 v[22:25], v[172:175], v[196:199], v[22:25]
	v_mfma_f32_16x16x32_bf16 v[10:13], v[160:163], v[204:207], v[10:13]
	v_mfma_f32_16x16x32_bf16 v[6:9], v[172:175], v[204:207], v[6:9]
	v_mfma_f32_16x16x32_bf16 v[70:73], v[176:179], v[184:187], v[46:49]
	v_mfma_f32_16x16x32_bf16 v[42:45], v[168:171], v[192:195], v[42:45]
	v_mfma_f32_16x16x32_bf16 v[38:41], v[176:179], v[192:195], v[38:41]
	v_mfma_f32_16x16x32_bf16 v[26:29], v[168:171], v[200:203], v[26:29]
	v_mfma_f32_16x16x32_bf16 v[22:25], v[176:179], v[200:203], v[22:25]
	v_mfma_f32_16x16x32_bf16 v[10:13], v[168:171], v[208:211], v[10:13]
	v_mfma_f32_16x16x32_bf16 v[6:9], v[176:179], v[208:211], v[6:9]
	s_setprio 0
	s_add_i32 s59, s59, 2
	s_add_u32 s26, s26, 0x100
	s_addc_u32 s27, s27, 0
	s_add_u32 s48, s48, 0x100
	s_addc_u32 s58, s58, 0
	s_add_u32 s28, s26, 0xfffc0080
	s_addc_u32 s29, s27, -1
	s_add_i32 s60, 0, 0x10000
	s_cmp_eq_u32 s59, 12
	s_cselect_b32 s31, s7, s29
	s_cselect_b32 s30, s19, s28
	s_cselect_b32 s29, s17, s58
	s_cselect_b32 s28, s25, s48
	s_add_i32 s62, 0, 0x14000
	s_cmp_gt_u32 s59, 13
	s_barrier
	s_cbranch_scc0 .LBB0_205
	s_and_b64 vcc, exec, s[14:15]
	s_cbranch_vccz .LBB0_208
	s_barrier

.LBB0_301:
	s_add_i32 s80, s38, 2
	s_add_u32 s81, s36, 0x80
	s_addc_u32 s39, s37, 0
	s_add_i32 s84, 0, 0x10000
	s_cmp_eq_u32 s31, s38
	s_cselect_b32 s39, s27, s39
	s_cselect_b32 s38, s26, s81
	s_waitcnt lgkmcnt(0)
	s_cselect_b32 s83, s29, s79
	s_cselect_b32 s82, s28, s78
	s_add_i32 s81, 0, 0x14000
	v_add_u32_e32 v146, s84, v206
	v_add_u32_e32 v162, s81, v206
	ds_read_b128 v[134:137], v146
	ds_read_b128 v[138:141], v146 offset:1024
	ds_read_b128 v[142:145], v146 offset:2048
	ds_read_b128 v[146:149], v146 offset:3072
	ds_read_b128 v[150:153], v162
	ds_read_b128 v[154:157], v162 offset:1024
	ds_read_b128 v[158:161], v162 offset:2048
	ds_read_b128 v[162:165], v162 offset:3072
	v_lshl_add_u64 v[202:203], s[36:37], 0, v[182:183]
	s_add_i32 m0, s44, 0xc000
	ds_read_b128 v[166:169], v209
	ds_read_b128 v[170:173], v209 offset:1024
	ds_read_b128 v[174:177], v209 offset:2048
	ds_read_b128 v[178:181], v209 offset:3072
	ds_read_b128 v[186:189], v209 offset:4096
	ds_read_b128 v[190:193], v209 offset:5120
	ds_read_b128 v[194:197], v209 offset:6144
	ds_read_b128 v[198:201], v209 offset:7168
	global_load_lds_dwordx4 v[202:203], off
	v_lshl_add_u64 v[202:203], s[36:37], 0, v[184:185]
	s_add_i32 m0, s44, 0xe000
	s_nop 0
	global_load_lds_dwordx4 v[202:203], off
	s_waitcnt vmcnt(8)
	s_waitcnt lgkmcnt(0)
	s_barrier
	s_setprio 1
	s_waitcnt lgkmcnt(0)
	v_mfma_f32_16x16x32_bf16 v[130:133], v[134:137], v[166:169], v[130:133]
	v_mfma_f32_16x16x32_bf16 v[126:129], v[142:145], v[166:169], v[126:129]
	v_mfma_f32_16x16x32_bf16 v[114:117], v[134:137], v[174:177], v[114:117]
	v_mfma_f32_16x16x32_bf16 v[110:113], v[142:145], v[174:177], v[110:113]
	v_mfma_f32_16x16x32_bf16 v[98:101], v[134:137], v[186:189], v[98:101]
	v_mfma_f32_16x16x32_bf16 v[94:97], v[142:145], v[186:189], v[94:97]
	v_mfma_f32_16x16x32_bf16 v[82:85], v[134:137], v[194:197], v[82:85]
	v_mfma_f32_16x16x32_bf16 v[78:81], v[142:145], v[194:197], v[78:81]
	v_mfma_f32_16x16x32_bf16 v[130:133], v[138:141], v[170:173], v[130:133]
	v_mfma_f32_16x16x32_bf16 v[126:129], v[146:149], v[170:173], v[126:129]
	v_mfma_f32_16x16x32_bf16 v[114:117], v[138:141], v[178:181], v[114:117]
	v_mfma_f32_16x16x32_bf16 v[110:113], v[146:149], v[178:181], v[110:113]
	v_mfma_f32_16x16x32_bf16 v[98:101], v[138:141], v[190:193], v[98:101]
	v_mfma_f32_16x16x32_bf16 v[94:97], v[146:149], v[190:193], v[94:97]
	v_mfma_f32_16x16x32_bf16 v[82:85], v[138:141], v[198:201], v[82:85]
	v_mfma_f32_16x16x32_bf16 v[78:81], v[146:149], v[198:201], v[78:81]
	s_setprio 0
	s_setprio 1
	v_mfma_f32_16x16x32_bf16 v[122:125], v[150:153], v[166:169], v[122:125]
	v_mfma_f32_16x16x32_bf16 v[118:121], v[158:161], v[166:169], v[118:121]
	v_mfma_f32_16x16x32_bf16 v[106:109], v[150:153], v[174:177], v[106:109]
	v_mfma_f32_16x16x32_bf16 v[102:105], v[158:161], v[174:177], v[102:105]
	v_mfma_f32_16x16x32_bf16 v[90:93], v[150:153], v[186:189], v[90:93]
	v_mfma_f32_16x16x32_bf16 v[86:89], v[158:161], v[186:189], v[86:89]
	v_mfma_f32_16x16x32_bf16 v[74:77], v[150:153], v[194:197], v[74:77]
	v_mfma_f32_16x16x32_bf16 v[70:73], v[158:161], v[194:197], v[70:73]
	v_mfma_f32_16x16x32_bf16 v[122:125], v[154:157], v[170:173], v[122:125]
	v_mfma_f32_16x16x32_bf16 v[118:121], v[162:165], v[170:173], v[118:121]
	v_mfma_f32_16x16x32_bf16 v[106:109], v[154:157], v[178:181], v[106:109]
	v_mfma_f32_16x16x32_bf16 v[102:105], v[162:165], v[178:181], v[102:105]
	v_mfma_f32_16x16x32_bf16 v[90:93], v[154:157], v[190:193], v[90:93]
	v_mfma_f32_16x16x32_bf16 v[86:89], v[162:165], v[190:193], v[86:89]
	v_mfma_f32_16x16x32_bf16 v[74:77], v[154:157], v[198:201], v[74:77]
	v_mfma_f32_16x16x32_bf16 v[70:73], v[162:165], v[198:201], v[70:73]
	s_setprio 0
	s_barrier
	s_add_i32 s84, s84, s43
	v_lshl_add_u64 v[202:203], s[82:83], 0, v[0:1]
	s_mov_b32 m0, s84
	ds_read_b128 v[166:169], v209 offset:16384
	ds_read_b128 v[170:173], v209 offset:17408
	ds_read_b128 v[174:177], v209 offset:18432
	ds_read_b128 v[178:181], v209 offset:19456
	ds_read_b128 v[186:189], v209 offset:20480
	ds_read_b128 v[190:193], v209 offset:21504
	ds_read_b128 v[194:197], v209 offset:22528
	ds_read_b128 v[198:201], v209 offset:23552
	global_load_lds_dwordx4 v[202:203], off
	s_add_i32 m0, s84, 0x2000
	v_lshl_add_u64 v[204:205], s[82:83], 0, v[2:3]
	s_add_u32 s82, s82, s48
	s_addc_u32 s83, s83, 0
	s_add_i32 s81, s81, s43
	global_load_lds_dwordx4 v[204:205], off
	v_lshl_add_u64 v[210:211], s[82:83], 0, v[0:1]
	s_mov_b32 m0, s81
	v_lshl_add_u64 v[212:213], s[82:83], 0, v[2:3]
	global_load_lds_dwordx4 v[210:211], off
	s_add_i32 m0, s81, 0x2000
	v_lshl_add_u64 v[214:215], s[38:39], 0, v[0:1]
	global_load_lds_dwordx4 v[212:213], off
	s_mov_b32 m0, s44
	v_lshl_add_u64 v[216:217], s[38:39], 0, v[2:3]
	global_load_lds_dwordx4 v[214:215], off
	s_mov_b32 m0, s45
	s_nop 0
	global_load_lds_dwordx4 v[216:217], off
	s_waitcnt vmcnt(8)
	s_waitcnt lgkmcnt(0)
	s_barrier
	s_setprio 1
	s_waitcnt lgkmcnt(0)
	v_mfma_f32_16x16x32_bf16 v[66:69], v[134:137], v[166:169], v[66:69]
	v_mfma_f32_16x16x32_bf16 v[62:65], v[142:145], v[166:169], v[62:65]
	v_mfma_f32_16x16x32_bf16 v[50:53], v[134:137], v[174:177], v[50:53]
	v_mfma_f32_16x16x32_bf16 v[46:49], v[142:145], v[174:177], v[46:49]
	v_mfma_f32_16x16x32_bf16 v[34:37], v[134:137], v[186:189], v[34:37]
	v_mfma_f32_16x16x32_bf16 v[30:33], v[142:145], v[186:189], v[30:33]
	v_mfma_f32_16x16x32_bf16 v[18:21], v[134:137], v[194:197], v[18:21]
	v_mfma_f32_16x16x32_bf16 v[14:17], v[142:145], v[194:197], v[14:17]
	v_mfma_f32_16x16x32_bf16 v[66:69], v[138:141], v[170:173], v[66:69]
	v_mfma_f32_16x16x32_bf16 v[62:65], v[146:149], v[170:173], v[62:65]
	v_mfma_f32_16x16x32_bf16 v[50:53], v[138:141], v[178:181], v[50:53]
	v_mfma_f32_16x16x32_bf16 v[46:49], v[146:149], v[178:181], v[46:49]
	v_mfma_f32_16x16x32_bf16 v[34:37], v[138:141], v[190:193], v[34:37]
	v_mfma_f32_16x16x32_bf16 v[30:33], v[146:149], v[190:193], v[30:33]
	v_mfma_f32_16x16x32_bf16 v[18:21], v[138:141], v[198:201], v[18:21]
	v_mfma_f32_16x16x32_bf16 v[14:17], v[146:149], v[198:201], v[14:17]
	s_setprio 0
	s_setprio 1
	v_mfma_f32_16x16x32_bf16 v[58:61], v[150:153], v[166:169], v[58:61]
	v_mfma_f32_16x16x32_bf16 v[54:57], v[158:161], v[166:169], v[54:57]
	v_mfma_f32_16x16x32_bf16 v[42:45], v[150:153], v[174:177], v[42:45]
	v_mfma_f32_16x16x32_bf16 v[38:41], v[158:161], v[174:177], v[38:41]
	v_mfma_f32_16x16x32_bf16 v[26:29], v[150:153], v[186:189], v[26:29]
	v_mfma_f32_16x16x32_bf16 v[22:25], v[158:161], v[186:189], v[22:25]
	v_mfma_f32_16x16x32_bf16 v[10:13], v[150:153], v[194:197], v[10:13]
	v_mfma_f32_16x16x32_bf16 v[6:9], v[158:161], v[194:197], v[6:9]
	v_mfma_f32_16x16x32_bf16 v[58:61], v[154:157], v[170:173], v[58:61]
	v_mfma_f32_16x16x32_bf16 v[54:57], v[162:165], v[170:173], v[54:57]
	v_mfma_f32_16x16x32_bf16 v[42:45], v[154:157], v[178:181], v[42:45]
	v_mfma_f32_16x16x32_bf16 v[38:41], v[162:165], v[178:181], v[38:41]
	v_mfma_f32_16x16x32_bf16 v[26:29], v[154:157], v[190:193], v[26:29]
	v_mfma_f32_16x16x32_bf16 v[22:25], v[162:165], v[190:193], v[22:25]
	v_mfma_f32_16x16x32_bf16 v[10:13], v[154:157], v[198:201], v[10:13]
	v_mfma_f32_16x16x32_bf16 v[6:9], v[162:165], v[198:201], v[6:9]
	s_setprio 0
	s_barrier
	s_add_i32 s81, 0, 0x18000
	s_add_i32 s82, 0, 0x1c000
	v_add_u32_e32 v146, s81, v206
	v_add_u32_e32 v162, s82, v206
	ds_read_b128 v[134:137], v146
	ds_read_b128 v[138:141], v146 offset:1024
	ds_read_b128 v[142:145], v146 offset:2048
	ds_read_b128 v[146:149], v146 offset:3072
	ds_read_b128 v[150:153], v162
	ds_read_b128 v[154:157], v162 offset:1024
	ds_read_b128 v[158:161], v162 offset:2048
	ds_read_b128 v[162:165], v162 offset:3072
	s_add_u32 s38, s38, s48
	s_addc_u32 s39, s39, 0
	s_mov_b32 m0, s58
	v_lshl_add_u64 v[220:221], s[38:39], 0, v[0:1]
	ds_read_b128 v[166:169], v209 offset:32768
	ds_read_b128 v[170:173], v209 offset:33792
	ds_read_b128 v[174:177], v209 offset:34816
	ds_read_b128 v[178:181], v209 offset:35840
	ds_read_b128 v[186:189], v209 offset:36864
	ds_read_b128 v[190:193], v209 offset:37888
	ds_read_b128 v[194:197], v209 offset:38912
	ds_read_b128 v[198:201], v209 offset:39936
	global_load_lds_dwordx4 v[220:221], off
	v_lshl_add_u64 v[220:221], s[38:39], 0, v[2:3]
	s_mov_b32 m0, s59
	s_nop 0
	global_load_lds_dwordx4 v[220:221], off
	s_waitcnt vmcnt(8)
	s_waitcnt lgkmcnt(0)
	s_barrier
	s_setprio 1
	s_waitcnt lgkmcnt(0)
	v_mfma_f32_16x16x32_bf16 v[130:133], v[134:137], v[166:169], v[130:133]
	v_mfma_f32_16x16x32_bf16 v[126:129], v[142:145], v[166:169], v[126:129]
	v_mfma_f32_16x16x32_bf16 v[114:117], v[134:137], v[174:177], v[114:117]
	v_mfma_f32_16x16x32_bf16 v[110:113], v[142:145], v[174:177], v[110:113]
	v_mfma_f32_16x16x32_bf16 v[98:101], v[134:137], v[186:189], v[98:101]
	v_mfma_f32_16x16x32_bf16 v[94:97], v[142:145], v[186:189], v[94:97]
	v_mfma_f32_16x16x32_bf16 v[82:85], v[134:137], v[194:197], v[82:85]
	v_mfma_f32_16x16x32_bf16 v[78:81], v[142:145], v[194:197], v[78:81]
	v_mfma_f32_16x16x32_bf16 v[130:133], v[138:141], v[170:173], v[130:133]
	v_mfma_f32_16x16x32_bf16 v[126:129], v[146:149], v[170:173], v[126:129]
	v_mfma_f32_16x16x32_bf16 v[114:117], v[138:141], v[178:181], v[114:117]
	v_mfma_f32_16x16x32_bf16 v[110:113], v[146:149], v[178:181], v[110:113]
	v_mfma_f32_16x16x32_bf16 v[98:101], v[138:141], v[190:193], v[98:101]
	v_mfma_f32_16x16x32_bf16 v[94:97], v[146:149], v[190:193], v[94:97]
	v_mfma_f32_16x16x32_bf16 v[82:85], v[138:141], v[198:201], v[82:85]
	v_mfma_f32_16x16x32_bf16 v[78:81], v[146:149], v[198:201], v[78:81]
	s_setprio 0
	s_setprio 1
	v_mfma_f32_16x16x32_bf16 v[122:125], v[150:153], v[166:169], v[122:125]
	v_mfma_f32_16x16x32_bf16 v[118:121], v[158:161], v[166:169], v[118:121]
	v_mfma_f32_16x16x32_bf16 v[106:109], v[150:153], v[174:177], v[106:109]
	v_mfma_f32_16x16x32_bf16 v[102:105], v[158:161], v[174:177], v[102:105]
	v_mfma_f32_16x16x32_bf16 v[90:93], v[150:153], v[186:189], v[90:93]
	v_mfma_f32_16x16x32_bf16 v[86:89], v[158:161], v[186:189], v[86:89]
	v_mfma_f32_16x16x32_bf16 v[74:77], v[150:153], v[194:197], v[74:77]
	v_mfma_f32_16x16x32_bf16 v[70:73], v[158:161], v[194:197], v[70:73]
	v_mfma_f32_16x16x32_bf16 v[122:125], v[154:157], v[170:173], v[122:125]
	v_mfma_f32_16x16x32_bf16 v[118:121], v[162:165], v[170:173], v[118:121]
	v_mfma_f32_16x16x32_bf16 v[106:109], v[154:157], v[178:181], v[106:109]
	v_mfma_f32_16x16x32_bf16 v[102:105], v[162:165], v[178:181], v[102:105]
	v_mfma_f32_16x16x32_bf16 v[90:93], v[154:157], v[190:193], v[90:93]
	v_mfma_f32_16x16x32_bf16 v[86:89], v[162:165], v[190:193], v[86:89]
	v_mfma_f32_16x16x32_bf16 v[74:77], v[154:157], v[198:201], v[74:77]
	v_mfma_f32_16x16x32_bf16 v[70:73], v[162:165], v[198:201], v[70:73]
	s_setprio 0
	s_barrier
	s_add_i32 s38, s81, s43
	v_lshl_add_u64 v[202:203], v[202:203], 0, s[50:51]
	s_mov_b32 m0, s38
	ds_read_b128 v[166:169], v209 offset:49152
	ds_read_b128 v[170:173], v209 offset:50176
	ds_read_b128 v[174:177], v209 offset:51200
	ds_read_b128 v[178:181], v209 offset:52224
	ds_read_b128 v[186:189], v209 offset:53248
	ds_read_b128 v[190:193], v209 offset:54272
	ds_read_b128 v[194:197], v209 offset:55296
	ds_read_b128 v[198:201], v209 offset:56320
	global_load_lds_dwordx4 v[202:203], off
	v_lshl_add_u64 v[202:203], v[204:205], 0, s[50:51]
	s_add_i32 m0, s38, 0x2000
	s_add_i32 s38, s82, s43
	global_load_lds_dwordx4 v[202:203], off
	v_lshl_add_u64 v[202:203], v[210:211], 0, s[50:51]
	s_mov_b32 m0, s38
	s_nop 0
	global_load_lds_dwordx4 v[202:203], off
	v_lshl_add_u64 v[202:203], v[212:213], 0, s[50:51]
	s_add_i32 m0, s38, 0x2000
	s_nop 0
	global_load_lds_dwordx4 v[202:203], off
	v_lshl_add_u64 v[202:203], v[214:215], 0, s[50:51]
	s_mov_b32 m0, s63
	s_nop 0
	global_load_lds_dwordx4 v[202:203], off
	v_lshl_add_u64 v[202:203], v[216:217], 0, s[50:51]
	s_mov_b32 m0, s64
	s_nop 0
	global_load_lds_dwordx4 v[202:203], off
	s_waitcnt vmcnt(8)
	s_waitcnt lgkmcnt(0)
	s_barrier
	s_setprio 1
	s_waitcnt lgkmcnt(0)
	v_mfma_f32_16x16x32_bf16 v[66:69], v[134:137], v[166:169], v[66:69]
	v_mfma_f32_16x16x32_bf16 v[62:65], v[142:145], v[166:169], v[62:65]
	v_mfma_f32_16x16x32_bf16 v[50:53], v[134:137], v[174:177], v[50:53]
	v_mfma_f32_16x16x32_bf16 v[46:49], v[142:145], v[174:177], v[46:49]
	v_mfma_f32_16x16x32_bf16 v[34:37], v[134:137], v[186:189], v[34:37]
	v_mfma_f32_16x16x32_bf16 v[30:33], v[142:145], v[186:189], v[30:33]
	v_mfma_f32_16x16x32_bf16 v[18:21], v[134:137], v[194:197], v[18:21]
	v_mfma_f32_16x16x32_bf16 v[14:17], v[142:145], v[194:197], v[14:17]
	v_mfma_f32_16x16x32_bf16 v[66:69], v[138:141], v[170:173], v[66:69]
	v_mfma_f32_16x16x32_bf16 v[62:65], v[146:149], v[170:173], v[62:65]
	v_mfma_f32_16x16x32_bf16 v[50:53], v[138:141], v[178:181], v[50:53]
	v_mfma_f32_16x16x32_bf16 v[46:49], v[146:149], v[178:181], v[46:49]
	v_mfma_f32_16x16x32_bf16 v[34:37], v[138:141], v[190:193], v[34:37]
	v_mfma_f32_16x16x32_bf16 v[30:33], v[146:149], v[190:193], v[30:33]
	v_mfma_f32_16x16x32_bf16 v[18:21], v[138:141], v[198:201], v[18:21]
	v_mfma_f32_16x16x32_bf16 v[14:17], v[146:149], v[198:201], v[14:17]
	s_setprio 0
	s_setprio 1
	v_mfma_f32_16x16x32_bf16 v[58:61], v[150:153], v[166:169], v[58:61]
	v_mfma_f32_16x16x32_bf16 v[54:57], v[158:161], v[166:169], v[54:57]
	v_mfma_f32_16x16x32_bf16 v[42:45], v[150:153], v[174:177], v[42:45]
	v_mfma_f32_16x16x32_bf16 v[38:41], v[158:161], v[174:177], v[38:41]
	v_mfma_f32_16x16x32_bf16 v[26:29], v[150:153], v[186:189], v[26:29]
	v_mfma_f32_16x16x32_bf16 v[22:25], v[158:161], v[186:189], v[22:25]
	v_mfma_f32_16x16x32_bf16 v[10:13], v[150:153], v[194:197], v[10:13]
	v_mfma_f32_16x16x32_bf16 v[6:9], v[158:161], v[194:197], v[6:9]
	v_mfma_f32_16x16x32_bf16 v[58:61], v[154:157], v[170:173], v[58:61]
	v_mfma_f32_16x16x32_bf16 v[54:57], v[162:165], v[170:173], v[54:57]
	v_mfma_f32_16x16x32_bf16 v[42:45], v[154:157], v[178:181], v[42:45]
	v_mfma_f32_16x16x32_bf16 v[38:41], v[162:165], v[178:181], v[38:41]
	v_mfma_f32_16x16x32_bf16 v[26:29], v[154:157], v[190:193], v[26:29]
	v_mfma_f32_16x16x32_bf16 v[22:25], v[162:165], v[190:193], v[22:25]
	v_mfma_f32_16x16x32_bf16 v[10:13], v[154:157], v[198:201], v[10:13]
	v_mfma_f32_16x16x32_bf16 v[6:9], v[162:165], v[198:201], v[6:9]
	s_setprio 0
	s_add_u32 s36, s36, 0x100
	s_addc_u32 s37, s37, 0
	s_add_u32 s78, s78, 0x100
	s_addc_u32 s79, s79, 0
	s_cmp_ge_i32 s80, s25
	s_mov_b32 s38, s80
	s_barrier
	s_cbranch_scc0 .LBB0_301
	s_load_dwordx2 s[82:83], s[54:55], 0xe0
	v_readlane_b32 s80, v253, 39
	v_readlane_b32 s84, v253, 44
	v_readlane_b32 s81, v253, 40
	s_and_b64 vcc, exec, s[20:21]
	s_cbranch_vccz .LBB0_304

.LBB0_346:
	s_ashr_i32 s27, s26, 31
	s_lshl_b64 s[28:29], s[26:27], 19
	s_add_u32 s28, s80, s28
	s_addc_u32 s29, s81, s29
	s_and_b64 s[30:31], s[4:5], exec
	s_cselect_b32 s3, s29, s9
	s_cselect_b32 s7, s28, s8
	s_ashr_i32 s25, s24, 31
	s_lshl_b64 s[30:31], s[24:25], 19
	s_add_u32 s30, s48, s30
	s_addc_u32 s31, s59, s31
	s_and_b64 s[36:37], s[4:5], exec
	s_cselect_b32 s25, s31, s35
	s_cselect_b32 s27, s30, s34
	s_add_u32 s8, s8, 0x40080
	s_addc_u32 s9, s9, 0
	s_add_u32 s33, s34, 0x100
	v_mov_b32_e32 v8, 0
	s_addc_u32 s38, s35, 0
	s_mov_b32 s39, -2
	v_mov_b32_e32 v9, v8
	v_mov_b32_e32 v10, v8
	v_mov_b32_e32 v11, v8
	v_mov_b32_e32 v12, v8
	v_mov_b32_e32 v13, v8
	v_mov_b32_e32 v14, v8
	v_mov_b32_e32 v15, v8
	v_mov_b32_e32 v24, v8
	v_mov_b32_e32 v25, v8
	v_mov_b32_e32 v26, v8
	v_mov_b32_e32 v27, v8
	v_mov_b32_e32 v28, v8
	v_mov_b32_e32 v29, v8
	v_mov_b32_e32 v30, v8
	v_mov_b32_e32 v31, v8
	v_mov_b32_e32 v56, v8
	v_mov_b32_e32 v57, v8
	v_mov_b32_e32 v58, v8
	v_mov_b32_e32 v59, v8
	v_mov_b32_e32 v60, v8
	v_mov_b32_e32 v61, v8
	v_mov_b32_e32 v62, v8
	v_mov_b32_e32 v63, v8
	v_mov_b32_e32 v96, v8
	v_mov_b32_e32 v97, v8
	v_mov_b32_e32 v98, v8
	v_mov_b32_e32 v99, v8
	v_mov_b32_e32 v100, v8
	v_mov_b32_e32 v101, v8
	v_mov_b32_e32 v102, v8
	v_mov_b32_e32 v103, v8
	v_mov_b32_e32 v16, v8
	v_mov_b32_e32 v17, v8
	v_mov_b32_e32 v18, v8
	v_mov_b32_e32 v19, v8
	v_mov_b32_e32 v20, v8
	v_mov_b32_e32 v21, v8
	v_mov_b32_e32 v22, v8
	v_mov_b32_e32 v23, v8
	v_mov_b32_e32 v32, v8
	v_mov_b32_e32 v33, v8
	v_mov_b32_e32 v34, v8
	v_mov_b32_e32 v35, v8
	v_mov_b32_e32 v36, v8
	v_mov_b32_e32 v37, v8
	v_mov_b32_e32 v38, v8
	v_mov_b32_e32 v39, v8
	v_mov_b32_e32 v72, v8
	v_mov_b32_e32 v73, v8
	v_mov_b32_e32 v74, v8
	v_mov_b32_e32 v75, v8
	v_mov_b32_e32 v76, v8
	v_mov_b32_e32 v77, v8
	v_mov_b32_e32 v78, v8
	v_mov_b32_e32 v79, v8
	v_mov_b32_e32 v104, v8
	v_mov_b32_e32 v105, v8
	v_mov_b32_e32 v106, v8
	v_mov_b32_e32 v107, v8
	v_mov_b32_e32 v108, v8
	v_mov_b32_e32 v109, v8
	v_mov_b32_e32 v110, v8
	v_mov_b32_e32 v111, v8
	v_mov_b32_e32 v112, v8
	v_mov_b32_e32 v113, v8
	v_mov_b32_e32 v114, v8
	v_mov_b32_e32 v115, v8
	v_mov_b32_e32 v116, v8
	v_mov_b32_e32 v117, v8
	v_mov_b32_e32 v118, v8
	v_mov_b32_e32 v119, v8
	v_mov_b32_e32 v128, v8
	v_mov_b32_e32 v129, v8
	v_mov_b32_e32 v130, v8
	v_mov_b32_e32 v131, v8
	v_mov_b32_e32 v132, v8
	v_mov_b32_e32 v133, v8
	v_mov_b32_e32 v134, v8
	v_mov_b32_e32 v135, v8
	v_mov_b32_e32 v144, v8
	v_mov_b32_e32 v145, v8
	v_mov_b32_e32 v146, v8
	v_mov_b32_e32 v147, v8
	v_mov_b32_e32 v148, v8
	v_mov_b32_e32 v149, v8
	v_mov_b32_e32 v150, v8
	v_mov_b32_e32 v151, v8
	v_mov_b32_e32 v160, v8
	v_mov_b32_e32 v161, v8
	v_mov_b32_e32 v162, v8
	v_mov_b32_e32 v163, v8
	v_mov_b32_e32 v164, v8
	v_mov_b32_e32 v165, v8
	v_mov_b32_e32 v166, v8
	v_mov_b32_e32 v167, v8
	v_mov_b32_e32 v120, v8
	v_mov_b32_e32 v121, v8
	v_mov_b32_e32 v122, v8
	v_mov_b32_e32 v123, v8
	v_mov_b32_e32 v124, v8
	v_mov_b32_e32 v125, v8
	v_mov_b32_e32 v126, v8
	v_mov_b32_e32 v127, v8
	v_mov_b32_e32 v136, v8
	v_mov_b32_e32 v137, v8
	v_mov_b32_e32 v138, v8
	v_mov_b32_e32 v139, v8
	v_mov_b32_e32 v140, v8
	v_mov_b32_e32 v141, v8
	v_mov_b32_e32 v142, v8
	v_mov_b32_e32 v143, v8
	v_mov_b32_e32 v152, v8
	v_mov_b32_e32 v153, v8
	v_mov_b32_e32 v154, v8
	v_mov_b32_e32 v155, v8
	v_mov_b32_e32 v156, v8
	v_mov_b32_e32 v157, v8
	v_mov_b32_e32 v158, v8
	v_mov_b32_e32 v159, v8
	v_mov_b32_e32 v168, v8
	v_mov_b32_e32 v169, v8
	v_mov_b32_e32 v170, v8
	v_mov_b32_e32 v171, v8
	v_mov_b32_e32 v172, v8
	v_mov_b32_e32 v173, v8
	v_mov_b32_e32 v174, v8
	v_mov_b32_e32 v175, v8
	s_add_u32 s34, s8, 0xfffc0080
	s_addc_u32 s35, s9, -1
	s_add_i32 s41, 0, 0x10000
	s_cmp_eq_u32 s39, 12
	s_cselect_b32 s37, s3, s35
	s_cselect_b32 s36, s7, s34
	s_cselect_b32 s35, s25, s38
	s_cselect_b32 s34, s27, s33
	s_add_i32 s44, 0, 0x14000
.LBB0_347:
	v_add_u32_e32 v0, s41, v243
	ds_read_b128 v[40:43], v0
	ds_read_b128 v[44:47], v0 offset:1024
	ds_read_b128 v[48:51], v0 offset:2048
	ds_read_b128 v[52:55], v0 offset:3072
	v_add_u32_e32 v0, s44, v243
	s_waitcnt vmcnt(0)
	ds_read_b128 v[64:67], v0
	ds_read_b128 v[68:71], v0 offset:1024
	ds_read_b128 v[80:83], v0 offset:2048
	ds_read_b128 v[84:87], v0 offset:3072
	v_lshl_add_u64 v[2:3], s[8:9], 0, v[198:199]
	s_add_i32 m0, s61, 0xc000
	ds_read_b128 v[88:91], v244
	ds_read_b128 v[92:95], v244 offset:1024
	ds_read_b128 v[176:179], v244 offset:2048
	ds_read_b128 v[180:183], v244 offset:3072
	ds_read_b128 v[202:205], v244 offset:4096
	ds_read_b128 v[206:209], v244 offset:5120
	ds_read_b128 v[210:213], v244 offset:6144
	ds_read_b128 v[220:223], v244 offset:7168
	global_load_lds_dwordx4 v[2:3], off
	v_lshl_add_u64 v[2:3], s[8:9], 0, v[200:201]
	s_add_i32 m0, s61, 0xe000
	s_nop 0
	global_load_lds_dwordx4 v[2:3], off
	s_waitcnt vmcnt(8)
	s_waitcnt lgkmcnt(0)
	s_barrier
	s_setprio 1
	s_waitcnt lgkmcnt(0)
	v_mfma_f32_16x16x32_bf16 v[172:175], v[40:43], v[88:91], v[172:175]
	v_mfma_f32_16x16x32_bf16 v[168:171], v[48:51], v[88:91], v[168:171]
	v_mfma_f32_16x16x32_bf16 v[156:159], v[40:43], v[176:179], v[156:159]
	v_mfma_f32_16x16x32_bf16 v[152:155], v[48:51], v[176:179], v[152:155]
	v_mfma_f32_16x16x32_bf16 v[140:143], v[40:43], v[202:205], v[140:143]
	v_mfma_f32_16x16x32_bf16 v[136:139], v[48:51], v[202:205], v[136:139]
	v_mfma_f32_16x16x32_bf16 v[124:127], v[40:43], v[210:213], v[124:127]
	v_mfma_f32_16x16x32_bf16 v[120:123], v[48:51], v[210:213], v[120:123]
	v_mfma_f32_16x16x32_bf16 v[172:175], v[44:47], v[92:95], v[172:175]
	v_mfma_f32_16x16x32_bf16 v[168:171], v[52:55], v[92:95], v[168:171]
	v_mfma_f32_16x16x32_bf16 v[156:159], v[44:47], v[180:183], v[156:159]
	v_mfma_f32_16x16x32_bf16 v[152:155], v[52:55], v[180:183], v[152:155]
	v_mfma_f32_16x16x32_bf16 v[140:143], v[44:47], v[206:209], v[140:143]
	v_mfma_f32_16x16x32_bf16 v[136:139], v[52:55], v[206:209], v[136:139]
	v_mfma_f32_16x16x32_bf16 v[124:127], v[44:47], v[220:223], v[124:127]
	v_mfma_f32_16x16x32_bf16 v[120:123], v[52:55], v[220:223], v[120:123]
	s_setprio 0
	s_setprio 1
	v_mfma_f32_16x16x32_bf16 v[164:167], v[64:67], v[88:91], v[164:167]
	v_mfma_f32_16x16x32_bf16 v[88:91], v[80:83], v[88:91], v[160:163]
	v_mfma_f32_16x16x32_bf16 v[144:147], v[80:83], v[176:179], v[144:147]
	v_mfma_f32_16x16x32_bf16 v[132:135], v[64:67], v[202:205], v[132:135]
	v_mfma_f32_16x16x32_bf16 v[128:131], v[80:83], v[202:205], v[128:131]
	v_mfma_f32_16x16x32_bf16 v[116:119], v[64:67], v[210:213], v[116:119]
	v_mfma_f32_16x16x32_bf16 v[112:115], v[80:83], v[210:213], v[112:115]
	v_mfma_f32_16x16x32_bf16 v[164:167], v[68:71], v[92:95], v[164:167]
	v_mfma_f32_16x16x32_bf16 v[88:91], v[84:87], v[92:95], v[88:91]
	v_mfma_f32_16x16x32_bf16 v[92:95], v[64:67], v[176:179], v[148:151]
	v_mfma_f32_16x16x32_bf16 v[144:147], v[84:87], v[180:183], v[144:147]
	v_mfma_f32_16x16x32_bf16 v[132:135], v[68:71], v[206:209], v[132:135]
	v_mfma_f32_16x16x32_bf16 v[128:131], v[84:87], v[206:209], v[128:131]
	v_mfma_f32_16x16x32_bf16 v[116:119], v[68:71], v[220:223], v[116:119]
	v_mfma_f32_16x16x32_bf16 v[112:115], v[84:87], v[220:223], v[112:115]
	v_mfma_f32_16x16x32_bf16 v[92:95], v[68:71], v[180:183], v[92:95]
	s_setprio 0
	s_barrier
	s_add_i32 s41, s41, s60
	v_lshl_add_u64 v[2:3], s[34:35], 0, v[186:187]
	s_mov_b32 m0, s41
	ds_read_b128 v[148:151], v244 offset:16384
	ds_read_b128 v[160:163], v244 offset:17408
	ds_read_b128 v[176:179], v244 offset:18432
	ds_read_b128 v[180:183], v244 offset:19456
	ds_read_b128 v[202:205], v244 offset:20480
	ds_read_b128 v[206:209], v244 offset:21504
	ds_read_b128 v[210:213], v244 offset:22528
	ds_read_b128 v[220:223], v244 offset:23552
	global_load_lds_dwordx4 v[2:3], off
	s_add_i32 m0, s41, 0x2000
	s_add_u32 s42, s34, 0x40000
	v_lshl_add_u64 v[214:215], s[34:35], 0, v[190:191]
	s_addc_u32 s43, s35, 0
	s_add_i32 s41, s44, s60
	global_load_lds_dwordx4 v[214:215], off
	v_lshl_add_u64 v[6:7], s[42:43], 0, v[186:187]
	s_mov_b32 m0, s41
	v_lshl_add_u64 v[216:217], s[36:37], 0, v[184:185]
	global_load_lds_dwordx4 v[6:7], off
	v_lshl_add_u64 v[6:7], s[42:43], 0, v[190:191]
	s_add_i32 m0, s41, 0x2000
	v_lshl_add_u64 v[228:229], s[36:37], 0, v[188:189]
	global_load_lds_dwordx4 v[6:7], off
	s_mov_b32 m0, s61
	s_nop 0
	global_load_lds_dwordx4 v[216:217], off
	s_mov_b32 m0, s62
	s_nop 0
	global_load_lds_dwordx4 v[228:229], off
	s_waitcnt vmcnt(8)
	s_waitcnt lgkmcnt(0)
	s_barrier
	s_setprio 1
	s_waitcnt lgkmcnt(0)
	v_mfma_f32_16x16x32_bf16 v[108:111], v[40:43], v[148:151], v[108:111]
	v_mfma_f32_16x16x32_bf16 v[104:107], v[48:51], v[148:151], v[104:107]
	v_mfma_f32_16x16x32_bf16 v[76:79], v[40:43], v[176:179], v[76:79]
	v_mfma_f32_16x16x32_bf16 v[72:75], v[48:51], v[176:179], v[72:75]
	v_mfma_f32_16x16x32_bf16 v[36:39], v[40:43], v[202:205], v[36:39]
	v_mfma_f32_16x16x32_bf16 v[32:35], v[48:51], v[202:205], v[32:35]
	v_mfma_f32_16x16x32_bf16 v[20:23], v[40:43], v[210:213], v[20:23]
	v_mfma_f32_16x16x32_bf16 v[16:19], v[48:51], v[210:213], v[16:19]
	v_mfma_f32_16x16x32_bf16 v[108:111], v[44:47], v[160:163], v[108:111]
	v_mfma_f32_16x16x32_bf16 v[104:107], v[52:55], v[160:163], v[104:107]
	v_mfma_f32_16x16x32_bf16 v[76:79], v[44:47], v[180:183], v[76:79]
	v_mfma_f32_16x16x32_bf16 v[72:75], v[52:55], v[180:183], v[72:75]
	v_mfma_f32_16x16x32_bf16 v[36:39], v[44:47], v[206:209], v[36:39]
	v_mfma_f32_16x16x32_bf16 v[32:35], v[52:55], v[206:209], v[32:35]
	v_mfma_f32_16x16x32_bf16 v[20:23], v[44:47], v[220:223], v[20:23]
	v_mfma_f32_16x16x32_bf16 v[16:19], v[52:55], v[220:223], v[16:19]
	s_setprio 0
	s_setprio 1
	v_mfma_f32_16x16x32_bf16 v[28:31], v[64:67], v[202:205], v[28:31]
	v_mfma_f32_16x16x32_bf16 v[24:27], v[80:83], v[202:205], v[24:27]
	v_mfma_f32_16x16x32_bf16 v[12:15], v[64:67], v[210:213], v[12:15]
	v_mfma_f32_16x16x32_bf16 v[6:9], v[80:83], v[210:213], v[8:11]
	v_mfma_f32_16x16x32_bf16 v[40:43], v[64:67], v[148:151], v[100:103]
	v_mfma_f32_16x16x32_bf16 v[44:47], v[80:83], v[148:151], v[96:99]
	v_mfma_f32_16x16x32_bf16 v[48:51], v[64:67], v[176:179], v[60:63]
	v_mfma_f32_16x16x32_bf16 v[52:55], v[80:83], v[176:179], v[56:59]
	v_mfma_f32_16x16x32_bf16 v[28:31], v[68:71], v[206:209], v[28:31]
	v_mfma_f32_16x16x32_bf16 v[24:27], v[84:87], v[206:209], v[24:27]
	v_mfma_f32_16x16x32_bf16 v[12:15], v[68:71], v[220:223], v[12:15]
	v_mfma_f32_16x16x32_bf16 v[6:9], v[84:87], v[220:223], v[6:9]
	v_mfma_f32_16x16x32_bf16 v[40:43], v[68:71], v[160:163], v[40:43]
	v_mfma_f32_16x16x32_bf16 v[44:47], v[84:87], v[160:163], v[44:47]
	v_mfma_f32_16x16x32_bf16 v[48:51], v[68:71], v[180:183], v[48:51]
	v_mfma_f32_16x16x32_bf16 v[52:55], v[84:87], v[180:183], v[52:55]
	s_setprio 0
	s_barrier
	s_add_i32 s41, 0, 0x18000
	v_add_u32_e32 v0, s41, v243
	s_add_i32 s42, 0, 0x1c000
	ds_read_b128 v[56:59], v0
	ds_read_b128 v[60:63], v0 offset:1024
	ds_read_b128 v[64:67], v0 offset:2048
	ds_read_b128 v[68:71], v0 offset:3072
	v_add_u32_e32 v0, s42, v243
	ds_read_b128 v[80:83], v0
	ds_read_b128 v[84:87], v0 offset:1024
	ds_read_b128 v[176:179], v0 offset:2048
	ds_read_b128 v[180:183], v0 offset:3072
	s_add_u32 s36, s36, 0x40000
	s_addc_u32 s37, s37, 0
	s_mov_b32 m0, s63
	v_lshl_add_u64 v[10:11], s[36:37], 0, v[184:185]
	ds_read_b128 v[96:99], v244 offset:32768
	ds_read_b128 v[100:103], v244 offset:33792
	ds_read_b128 v[202:205], v244 offset:34816
	ds_read_b128 v[206:209], v244 offset:35840
	ds_read_b128 v[210:213], v244 offset:36864
	ds_read_b128 v[220:223], v244 offset:37888
	ds_read_b128 v[224:227], v244 offset:38912
	ds_read_b128 v[246:249], v244 offset:39936
	global_load_lds_dwordx4 v[10:11], off
	v_lshl_add_u64 v[10:11], s[36:37], 0, v[188:189]
	s_mov_b32 m0, s64
	s_nop 0
	global_load_lds_dwordx4 v[10:11], off
	s_waitcnt vmcnt(8)
	s_waitcnt lgkmcnt(0)
	s_barrier
	s_setprio 1
	s_waitcnt lgkmcnt(0)
	v_mfma_f32_16x16x32_bf16 v[148:151], v[56:59], v[96:99], v[172:175]
	v_mfma_f32_16x16x32_bf16 v[172:175], v[60:63], v[100:103], v[148:151]
	v_mfma_f32_16x16x32_bf16 v[148:151], v[64:67], v[96:99], v[168:171]
	v_mfma_f32_16x16x32_bf16 v[168:171], v[68:71], v[100:103], v[148:151]
	v_mfma_f32_16x16x32_bf16 v[148:151], v[56:59], v[202:205], v[156:159]
	v_mfma_f32_16x16x32_bf16 v[156:159], v[60:63], v[206:209], v[148:151]
	v_mfma_f32_16x16x32_bf16 v[148:151], v[64:67], v[202:205], v[152:155]
	v_mfma_f32_16x16x32_bf16 v[140:143], v[56:59], v[210:213], v[140:143]
	v_mfma_f32_16x16x32_bf16 v[136:139], v[64:67], v[210:213], v[136:139]
	v_mfma_f32_16x16x32_bf16 v[124:127], v[56:59], v[224:227], v[124:127]
	v_mfma_f32_16x16x32_bf16 v[120:123], v[64:67], v[224:227], v[120:123]
	v_mfma_f32_16x16x32_bf16 v[152:155], v[68:71], v[206:209], v[148:151]
	v_mfma_f32_16x16x32_bf16 v[140:143], v[60:63], v[220:223], v[140:143]
	v_mfma_f32_16x16x32_bf16 v[136:139], v[68:71], v[220:223], v[136:139]
	v_mfma_f32_16x16x32_bf16 v[124:127], v[60:63], v[246:249], v[124:127]
	v_mfma_f32_16x16x32_bf16 v[120:123], v[68:71], v[246:249], v[120:123]
	s_setprio 0
	s_setprio 1
	v_mfma_f32_16x16x32_bf16 v[88:91], v[176:179], v[96:99], v[88:91]
	v_mfma_f32_16x16x32_bf16 v[148:151], v[80:83], v[96:99], v[164:167]
	v_mfma_f32_16x16x32_bf16 v[160:163], v[180:183], v[100:103], v[88:91]
	v_mfma_f32_16x16x32_bf16 v[88:91], v[80:83], v[202:205], v[92:95]
	v_mfma_f32_16x16x32_bf16 v[164:167], v[84:87], v[100:103], v[148:151]
	v_mfma_f32_16x16x32_bf16 v[148:151], v[84:87], v[206:209], v[88:91]
	v_mfma_f32_16x16x32_bf16 v[88:91], v[176:179], v[202:205], v[144:147]
	v_mfma_f32_16x16x32_bf16 v[144:147], v[180:183], v[206:209], v[88:91]
	v_mfma_f32_16x16x32_bf16 v[88:91], v[80:83], v[210:213], v[132:135]
	v_mfma_f32_16x16x32_bf16 v[132:135], v[84:87], v[220:223], v[88:91]
	v_mfma_f32_16x16x32_bf16 v[88:91], v[176:179], v[210:213], v[128:131]
	v_mfma_f32_16x16x32_bf16 v[128:131], v[180:183], v[220:223], v[88:91]
	v_mfma_f32_16x16x32_bf16 v[88:91], v[80:83], v[224:227], v[116:119]
	v_mfma_f32_16x16x32_bf16 v[116:119], v[84:87], v[246:249], v[88:91]
	v_mfma_f32_16x16x32_bf16 v[88:91], v[176:179], v[224:227], v[112:115]
	v_mfma_f32_16x16x32_bf16 v[112:115], v[180:183], v[246:249], v[88:91]
	s_setprio 0
	s_barrier
	s_add_i32 s36, s41, s60
	v_lshl_add_u64 v[2:3], v[2:3], 0, s[50:51]
	s_mov_b32 m0, s36
	s_nop 1
	ds_read_b128 v[88:91], v244 offset:49152
	ds_read_b128 v[92:95], v244 offset:50176
	ds_read_b128 v[202:205], v244 offset:51200
	ds_read_b128 v[206:209], v244 offset:52224
	ds_read_b128 v[210:213], v244 offset:53248
	ds_read_b128 v[220:223], v244 offset:54272
	ds_read_b128 v[224:227], v244 offset:55296
	ds_read_b128 v[246:249], v244 offset:56320
	global_load_lds_dwordx4 v[2:3], off
	s_add_i32 m0, s36, 0x2000
	s_add_u32 s34, s34, 0x40080
	v_lshl_add_u64 v[2:3], v[214:215], 0, s[50:51]
	s_addc_u32 s35, s35, 0
	s_add_i32 s36, s42, s60
	global_load_lds_dwordx4 v[2:3], off
	v_lshl_add_u64 v[2:3], s[34:35], 0, v[186:187]
	s_mov_b32 m0, s36
	s_nop 0
	global_load_lds_dwordx4 v[2:3], off
	v_lshl_add_u64 v[2:3], s[34:35], 0, v[190:191]
	s_add_i32 m0, s36, 0x2000
	s_nop 0
	global_load_lds_dwordx4 v[2:3], off
	v_lshl_add_u64 v[2:3], v[216:217], 0, s[50:51]
	s_mov_b32 m0, s74
	s_nop 0
	global_load_lds_dwordx4 v[2:3], off
	v_lshl_add_u64 v[2:3], v[228:229], 0, s[50:51]
	s_mov_b32 m0, s75
	s_nop 0
	global_load_lds_dwordx4 v[2:3], off
	s_waitcnt vmcnt(8)
	s_waitcnt lgkmcnt(0)
	s_barrier
	s_setprio 1
	s_waitcnt lgkmcnt(0)
	v_mfma_f32_16x16x32_bf16 v[96:99], v[56:59], v[88:91], v[108:111]
	v_mfma_f32_16x16x32_bf16 v[108:111], v[60:63], v[92:95], v[96:99]
	v_mfma_f32_16x16x32_bf16 v[96:99], v[64:67], v[88:91], v[104:107]
	v_mfma_f32_16x16x32_bf16 v[76:79], v[56:59], v[202:205], v[76:79]
	v_mfma_f32_16x16x32_bf16 v[72:75], v[64:67], v[202:205], v[72:75]
	v_mfma_f32_16x16x32_bf16 v[36:39], v[56:59], v[210:213], v[36:39]
	v_mfma_f32_16x16x32_bf16 v[32:35], v[64:67], v[210:213], v[32:35]
	v_mfma_f32_16x16x32_bf16 v[20:23], v[56:59], v[224:227], v[20:23]
	v_mfma_f32_16x16x32_bf16 v[16:19], v[64:67], v[224:227], v[16:19]
	v_mfma_f32_16x16x32_bf16 v[104:107], v[68:71], v[92:95], v[96:99]
	v_mfma_f32_16x16x32_bf16 v[76:79], v[60:63], v[206:209], v[76:79]
	v_mfma_f32_16x16x32_bf16 v[72:75], v[68:71], v[206:209], v[72:75]
	v_mfma_f32_16x16x32_bf16 v[36:39], v[60:63], v[220:223], v[36:39]
	v_mfma_f32_16x16x32_bf16 v[32:35], v[68:71], v[220:223], v[32:35]
	v_mfma_f32_16x16x32_bf16 v[20:23], v[60:63], v[246:249], v[20:23]
	v_mfma_f32_16x16x32_bf16 v[16:19], v[68:71], v[246:249], v[16:19]
	s_setprio 0
	s_setprio 1
	v_mfma_f32_16x16x32_bf16 v[40:43], v[80:83], v[88:91], v[40:43]
	v_mfma_f32_16x16x32_bf16 v[100:103], v[84:87], v[92:95], v[40:43]
	v_mfma_f32_16x16x32_bf16 v[40:43], v[176:179], v[88:91], v[44:47]
	v_mfma_f32_16x16x32_bf16 v[96:99], v[180:183], v[92:95], v[40:43]
	v_mfma_f32_16x16x32_bf16 v[40:43], v[80:83], v[202:205], v[48:51]
	v_mfma_f32_16x16x32_bf16 v[60:63], v[84:87], v[206:209], v[40:43]
	v_mfma_f32_16x16x32_bf16 v[40:43], v[176:179], v[202:205], v[52:55]
	v_mfma_f32_16x16x32_bf16 v[28:31], v[80:83], v[210:213], v[28:31]
	v_mfma_f32_16x16x32_bf16 v[24:27], v[176:179], v[210:213], v[24:27]
	v_mfma_f32_16x16x32_bf16 v[10:13], v[80:83], v[224:227], v[12:15]
	v_mfma_f32_16x16x32_bf16 v[6:9], v[176:179], v[224:227], v[6:9]
	v_mfma_f32_16x16x32_bf16 v[56:59], v[180:183], v[206:209], v[40:43]
	v_mfma_f32_16x16x32_bf16 v[28:31], v[84:87], v[220:223], v[28:31]
	v_mfma_f32_16x16x32_bf16 v[24:27], v[180:183], v[220:223], v[24:27]
	v_mfma_f32_16x16x32_bf16 v[12:15], v[84:87], v[246:249], v[10:13]
	v_mfma_f32_16x16x32_bf16 v[8:11], v[180:183], v[246:249], v[6:9]
	s_setprio 0
	s_add_i32 s39, s39, 2
	s_add_u32 s8, s8, 0x100
	s_addc_u32 s9, s9, 0
	s_add_u32 s33, s33, 0x100
	s_addc_u32 s38, s38, 0
	s_add_u32 s34, s8, 0xfffc0080
	s_addc_u32 s35, s9, -1
	s_add_i32 s41, 0, 0x10000
	s_cmp_eq_u32 s39, 12
	s_cselect_b32 s37, s3, s35
	s_cselect_b32 s36, s7, s34
	s_cselect_b32 s35, s25, s38
	s_cselect_b32 s34, s27, s33
	s_add_i32 s44, 0, 0x14000
	s_cmp_gt_u32 s39, 13
	s_barrier
	s_cbranch_scc0 .LBB0_347
	s_and_b64 vcc, exec, s[20:21]
	s_cbranch_vccz .LBB0_350
	s_barrier
